# gate_item even batched loads; attention V^T LDS row stride 136B (conflict-free ds_read2_b64)
# speedup vs baseline: 1.0733x; 1.0130x over previous
.LBB0_361:
	s_or_b64 exec, exec, s[0:1]
	s_waitcnt lgkmcnt(0)
	s_barrier
	ds_read_b32 v0, v230
	s_movk_i32 s0, 0x5ff
	s_waitcnt lgkmcnt(0)
	v_cmp_lt_i32_e64 s[0:1], s0, v0
	s_nop 1
	v_writelane_b32 v254, s0, 54
	v_lshl_add_u32 v4, v0, 1, v216
	v_cmp_gt_i32_e32 vcc, s21, v4
	v_writelane_b32 v254, s1, 55
	v_readfirstlane_b32 s0, v0
	s_cmpk_lt_i32 s0, 0x600
	s_cselect_b64 s[0:1], -1, 0
	s_and_b64 s[0:1], s[0:1], vcc
	s_and_saveexec_b64 s[92:93], s[0:1]
	s_cbranch_execz .LBB0_356
	v_add_u32_e32 v0, 0xfffff600, v4
	s_movk_i32 s0, 0xf6ff
	v_cmp_lt_u32_e32 vcc, s0, v0
	s_movk_i32 s0, 0xa00
	v_cmp_gt_i32_e64 s[0:1], s0, v4
	v_mov_b32_e32 v0, 0xfffff700
	s_nop 0
	v_cndmask_b32_e64 v0, v0, v236, s[0:1]
	v_add_u32_e32 v5, v0, v4
	s_and_saveexec_b64 s[0:1], vcc
	s_xor_b64 s[60:61], exec, s[0:1]
	s_cbranch_execz .LBB0_434
	s_movk_i32 s0, 0x7ff
	v_cmp_lt_i32_e32 vcc, s0, v5
	s_and_saveexec_b64 s[0:1], vcc
	s_xor_b64 s[0:1], exec, s[0:1]
	s_cbranch_execz .LBB0_380
	v_mov_b32_e32 v0, v217
	s_nop 0
	v_cmp_eq_u32_e32 vcc, 0, v0
	s_and_saveexec_b64 s[42:43], vcc
	ds_write_b32 v227, v17
	s_or_b64 exec, exec, s[42:43]
	v_add_u32_e32 v1, 0xfffff800, v5
	s_waitcnt vmcnt(1)
	v_lshlrev_b32_e32 v2, 4, v5
	v_lshrrev_b32_e32 v1, 4, v1
	v_and_b32_e32 v4, 3, v4
	v_and_b32_e32 v2, 0xc0, v2
	v_lshl_or_b32 v16, v1, 2, v4
	v_lshl_or_b32 v1, v1, 8, v2
	v_mov_b64_e32 v[2:3], s[30:31]
	v_mad_u64_u32 v[2:3], s[40:41], v1, s33, v[2:3]
	v_lshlrev_b32_e32 v4, 8, v4
	v_mov_b32_e32 v5, v17
	v_readlane_b32 s40, v254, 31
	v_lshl_add_u64 v[2:3], v[2:3], 0, v[4:5]
	v_lshlrev_b64 v[4:5], 16, v[16:17]
	v_readlane_b32 s41, v254, 32
	v_ashrrev_i32_e32 v100, 2, v0
	v_lshlrev_b32_e32 v14, 5, v0
	v_lshl_add_u64 v[6:7], s[40:41], 0, v[4:5]
	v_readlane_b32 s40, v254, 29
	v_ashrrev_i32_e32 v8, 1, v0
	v_ashrrev_i32_e32 v101, 31, v100
	v_and_b32_e32 v9, 0x60, v14
	v_readlane_b32 s41, v254, 30
	v_bfi_b32 v1, -16, v100, v0
	v_lshlrev_b64 v[10:11], 8, v[100:101]
	v_lshlrev_b32_e32 v102, 1, v9
	v_ashrrev_i32_e32 v9, 31, v8
	v_lshl_add_u64 v[4:5], s[40:41], 0, v[4:5]
	v_lshl_add_u64 v[10:11], v[6:7], 0, v[10:11]
	v_mov_b32_e32 v103, v17
	v_lshlrev_b64 v[12:13], 9, v[8:9]
	v_and_b32_e32 v9, 32, v14
	v_mad_i64_i32 v[108:109], s[40:41], v1, s33, v[2:3]
	v_and_b32_e32 v16, 48, v0
	v_lshl_add_u64 v[10:11], v[10:11], 0, v[102:103]
	v_lshl_add_u64 v[4:5], v[4:5], 0, v[12:13]
	v_lshlrev_b32_e32 v104, 1, v9
	v_mov_b32_e32 v105, v17
	v_lshl_add_u64 v[2:3], v[108:109], 0, v[16:17]
	v_lshl_add_u64 v[106:107], v[4:5], 0, v[104:105]
	global_load_dwordx4 v[24:27], v[10:11], off
	global_load_dwordx4 v[40:43], v[10:11], off offset:16
	global_load_dwordx4 v[48:51], v[106:107], off
	global_load_dwordx4 v[52:55], v[106:107], off offset:16
	global_load_dwordx4 v[60:63], v[10:11], off offset:32
	global_load_dwordx4 v[64:67], v[10:11], off offset:48
	global_load_dwordx4 v[68:71], v[106:107], off offset:32
	global_load_dwordx4 v[72:75], v[106:107], off offset:48
	global_load_dwordx4 v[28:31], v[2:3], off offset:3072
	global_load_dwordx4 v[32:35], v[2:3], off offset:3136
	global_load_dwordx4 v[36:39], v[2:3], off offset:3200
	global_load_dwordx4 v[44:47], v[2:3], off offset:3264
	v_and_b32_e32 v1, 63, v0
	v_and_b32_e32 v2, 15, v0
	v_bfe_u32 v0, v0, 4, 2
	s_movk_i32 s34, 0x88
	v_lshlrev_b32_e32 v110, 3, v0
	v_mul_lo_u32 v0, v100, s34
	s_movk_i32 s34, 0x44
	v_mul_lo_u32 v3, v8, s34
	v_mul_u32_u24_e32 v4, 0x88, v2
	s_movk_i32 s34, 0x4400
	v_lshlrev_b32_e32 v101, 1, v0
	v_lshlrev_b32_e32 v105, 1, v3
	v_add3_u32 v111, v4, v110, s34
	s_movk_i32 s34, 0x110
	v_mov_b32_e32 v18, v17
	v_mov_b32_e32 v19, v17
	v_add3_u32 v4, v194, v101, v102
	v_add3_u32 v5, v194, v105, v104
	v_mad_u32_u24 v114, v2, s34, v16
	v_mov_b32_e32 v16, v17
	v_cmp_eq_u32_e64 s[42:43], 0, v1
	v_lshl_add_u64 v[112:113], v[6:7], 0, v[102:103]
	v_mov_b64_e32 v[0:1], v[16:17]
	v_mov_b64_e32 v[8:9], v[16:17]
	v_mov_b64_e32 v[22:23], v[18:19]
	v_mov_b64_e32 v[58:59], v[18:19]
	v_mov_b64_e32 v[78:79], v[18:19]
	v_mov_b64_e32 v[82:83], v[18:19]
	v_mov_b64_e32 v[12:13], v[16:17]
	s_mov_b32 s46, 0
	v_mov_b32_e32 v117, 0xff800000
	v_mov_b32_e32 v115, 0
	v_mov_b64_e32 v[2:3], v[18:19]
	v_mov_b64_e32 v[10:11], v[18:19]
	v_mov_b64_e32 v[20:21], v[16:17]
	v_mov_b64_e32 v[56:57], v[16:17]
	v_mov_b64_e32 v[76:77], v[16:17]
	v_mov_b64_e32 v[80:81], v[16:17]
	v_mov_b64_e32 v[14:15], v[18:19]
	s_mov_b32 s48, 0
	s_waitcnt vmcnt(11)
	ds_write_b128 v4, v[24:27]
	s_waitcnt vmcnt(9)
	ds_write_b64 v5, v[48:49] offset:17408
	ds_write_b64 v5, v[50:51] offset:17416
	ds_write_b128 v4, v[40:43] offset:16
	s_waitcnt vmcnt(8)
	ds_write_b64 v5, v[52:53] offset:17424
	ds_write_b64 v5, v[54:55] offset:17432
	s_waitcnt vmcnt(7)
	ds_write_b128 v4, v[60:63] offset:32
	s_waitcnt vmcnt(5)
	ds_write_b64 v5, v[68:69] offset:17440
	ds_write_b64 v5, v[70:71] offset:17448
	ds_write_b128 v4, v[64:67] offset:48
	s_waitcnt vmcnt(4)
	ds_write_b64 v5, v[72:73] offset:17456
	ds_write_b64 v5, v[74:75] offset:17464
	v_mov_b64_e32 v[4:5], v[16:17]
	v_mov_b64_e32 v[6:7], v[18:19]
	s_waitcnt lgkmcnt(0)
	s_barrier

.LBB0_371:
	v_fma_f32 v84, v84, s94, -v116
	v_fma_f32 v85, v85, s94, -v116
	v_fma_f32 v86, v86, s94, -v116
	v_fma_f32 v87, v87, s94, -v116
	v_fma_f32 v96, v96, s94, -v116
	v_fma_f32 v97, v97, s94, -v116
	v_fma_f32 v98, v98, s94, -v116
	v_fma_f32 v99, v99, s94, -v116
	v_exp_f32_e32 v84, v84
	v_exp_f32_e32 v85, v85
	v_exp_f32_e32 v86, v86
	v_exp_f32_e32 v87, v87
	v_exp_f32_e32 v96, v96
	v_exp_f32_e32 v97, v97
	v_exp_f32_e32 v98, v98
	v_exp_f32_e32 v99, v99
	v_add_u32_e32 v18, v111, v18
	ds_read2_b64 v[126:129], v18 offset1:4
	ds_read2_b64 v[130:133], v18 offset0:8 offset1:12
	v_fma_f32 v88, v88, s94, -v116
	v_fma_f32 v89, v89, s94, -v116
	v_fma_f32 v90, v90, s94, -v116
	v_fma_f32 v91, v91, s94, -v116
	v_fma_f32 v92, v92, s94, -v116
	v_fma_f32 v93, v93, s94, -v116
	v_fma_f32 v94, v94, s94, -v116
	v_fma_f32 v95, v95, s94, -v116
	v_add_u32_e32 v117, 0x880, v18
	ds_read2_b64 v[134:137], v117 offset1:4
	v_exp_f32_e32 v88, v88
	v_exp_f32_e32 v89, v89
	v_exp_f32_e32 v90, v90
	v_exp_f32_e32 v91, v91
	v_exp_f32_e32 v92, v92
	v_exp_f32_e32 v93, v93
	v_exp_f32_e32 v94, v94
	v_exp_f32_e32 v95, v95
	v_cvt_pk_bf16_f32 v118, v84, v85
	v_cvt_pk_bf16_f32 v119, v86, v87
	v_cvt_pk_bf16_f32 v120, v96, v97
	v_cvt_pk_bf16_f32 v121, v98, v99
	ds_read2_b64 v[138:141], v117 offset0:8 offset1:12
	s_waitcnt lgkmcnt(3)
	v_add_u32_e32 v117, 0x1100, v18
	v_cvt_pk_bf16_f32 v122, v88, v89
	v_mfma_f32_16x16x32_bf16 v[80:83], v[126:129], v[118:121], v[80:83]
	ds_read2_b64 v[126:129], v117 offset1:4
	v_cvt_pk_bf16_f32 v123, v90, v91
	v_cvt_pk_bf16_f32 v124, v92, v93
	v_cvt_pk_bf16_f32 v125, v94, v95
	s_waitcnt lgkmcnt(3)
	s_andn2_b64 vcc, exec, s[44:45]
	s_nop 0
	v_mfma_f32_16x16x32_bf16 v[80:83], v[130:133], v[122:125], v[80:83]
	ds_read2_b64 v[130:133], v117 offset0:8 offset1:12
	s_waitcnt lgkmcnt(3)
	v_add_u32_e32 v117, 0x1980, v18
	v_mfma_f32_16x16x32_bf16 v[76:79], v[134:137], v[118:121], v[76:79]
	ds_read2_b64 v[134:137], v117 offset1:4
	s_waitcnt lgkmcnt(3)
	s_nop 0
	v_mfma_f32_16x16x32_bf16 v[76:79], v[138:141], v[122:125], v[76:79]
	ds_read2_b64 v[138:141], v117 offset0:8 offset1:12
	s_waitcnt lgkmcnt(3)
	v_add_u32_e32 v117, 0x2200, v18
	v_mfma_f32_16x16x32_bf16 v[56:59], v[126:129], v[118:121], v[56:59]
	ds_read2_b64 v[126:129], v117 offset1:4
	s_waitcnt lgkmcnt(3)
	s_nop 0
	v_mfma_f32_16x16x32_bf16 v[56:59], v[130:133], v[122:125], v[56:59]
	ds_read2_b64 v[130:133], v117 offset0:8 offset1:12
	s_waitcnt lgkmcnt(3)
	v_add_u32_e32 v117, 0x2a80, v18
	v_mfma_f32_16x16x32_bf16 v[20:23], v[134:137], v[118:121], v[20:23]
	ds_read2_b64 v[134:137], v117 offset1:4
	s_waitcnt lgkmcnt(3)
	s_nop 0
	v_mfma_f32_16x16x32_bf16 v[20:23], v[138:141], v[122:125], v[20:23]
	ds_read2_b64 v[138:141], v117 offset0:8 offset1:12
	s_waitcnt lgkmcnt(3)
	v_add_u32_e32 v117, 0x3300, v18
	v_mfma_f32_16x16x32_bf16 v[8:11], v[126:129], v[118:121], v[8:11]
	ds_read2_b64 v[126:129], v117 offset1:4
	s_waitcnt lgkmcnt(3)
	v_add_u32_e32 v18, 0x3b80, v18
	v_mfma_f32_16x16x32_bf16 v[8:11], v[130:133], v[122:125], v[8:11]
	ds_read2_b64 v[130:133], v117 offset0:8 offset1:12
	s_waitcnt lgkmcnt(3)
	s_nop 0
	v_mfma_f32_16x16x32_bf16 v[0:3], v[134:137], v[118:121], v[0:3]
	ds_read2_b64 v[134:137], v18 offset1:4
	s_waitcnt lgkmcnt(3)
	s_nop 0
	v_mfma_f32_16x16x32_bf16 v[0:3], v[138:141], v[122:125], v[0:3]
	ds_read2_b64 v[138:141], v18 offset0:8 offset1:12
	s_waitcnt lgkmcnt(3)
	s_waitcnt lgkmcnt(2)
	s_waitcnt lgkmcnt(1)
	s_nop 0
	v_mfma_f32_16x16x32_bf16 v[12:15], v[126:129], v[118:121], v[12:15]
	s_waitcnt lgkmcnt(0)
	v_mfma_f32_16x16x32_bf16 v[4:7], v[134:137], v[118:121], v[4:7]
	v_mfma_f32_16x16x32_bf16 v[12:15], v[130:133], v[122:125], v[12:15]
	v_mfma_f32_16x16x32_bf16 v[4:7], v[138:141], v[122:125], v[4:7]
	s_cbranch_vccnz .LBB0_373
	s_bitcmp1_b32 s49, 0
	s_cselect_b32 s34, 0x8c00, 0
	v_add_u32_e32 v18, s34, v194
	v_add3_u32 v117, v18, v101, v102
	v_add3_u32 v18, v18, v105, v104
	ds_write_b128 v117, v[24:27]
	ds_write_b64 v18, v[48:49] offset:17408
	ds_write_b64 v18, v[50:51] offset:17416
	ds_write_b128 v117, v[40:43] offset:16
	ds_write_b64 v18, v[52:53] offset:17424
	ds_write_b64 v18, v[54:55] offset:17432
	ds_write_b128 v117, v[60:63] offset:32
	ds_write_b64 v18, v[68:69] offset:17440
	ds_write_b64 v18, v[70:71] offset:17448
	ds_write_b128 v117, v[64:67] offset:48
	ds_write_b64 v18, v[72:73] offset:17456
	ds_write_b64 v18, v[74:75] offset:17464

.LBB0_380:
	s_andn2_saveexec_b64 s[62:63], s[0:1]
	s_cbranch_execz .LBB0_433
	v_mov_b32_e32 v0, v217
	s_nop 0
	v_cmp_eq_u32_e32 vcc, 0, v0
	s_and_saveexec_b64 s[0:1], vcc
	ds_write_b32 v227, v17
	s_or_b64 exec, exec, s[0:1]
	v_ashrrev_i32_e32 v1, 8, v5
	v_and_b32_e32 v11, 3, v4
	s_waitcnt vmcnt(1)
	v_lshl_or_b32 v2, v1, 2, v11
	s_mov_b32 s0, 0x90000
	v_mul_lo_u32 v2, v2, s0
	v_bfe_u32 v10, v4, 2, 6
	v_ashrrev_i32_e32 v3, 31, v2
	v_mov_b64_e32 v[4:5], 0x400000
	v_lshl_add_u64 v[2:3], v[2:3], 1, v[4:5]
	v_med3_u32 v4, v10, 4, 60
	v_readlane_b32 s0, v254, 31
	v_add_u32_e32 v128, -4, v4
	v_readlane_b32 s1, v254, 32
	v_ashrrev_i32_e32 v129, 2, v0
	v_lshl_add_u32 v6, v128, 6, v129
	v_lshl_add_u64 v[4:5], s[0:1], 0, v[2:3]
	v_readlane_b32 s0, v254, 29
	v_readlane_b32 s1, v254, 30
	v_ashrrev_i32_e32 v7, 31, v6
	v_lshlrev_b32_e32 v13, 5, v0
	v_lshl_add_u64 v[2:3], s[0:1], 0, v[2:3]
	v_ashrrev_i32_e32 v12, 1, v0
	v_lshlrev_b64 v[6:7], 8, v[6:7]
	v_and_b32_e32 v8, 0x60, v13
	s_movk_i32 s0, 0x2400
	v_lshl_add_u64 v[6:7], v[4:5], 0, v[6:7]
	v_lshlrev_b32_e32 v116, 1, v8
	v_mov_b32_e32 v117, v17
	v_mad_i64_i32 v[2:3], s[0:1], v12, s0, v[2:3]
	v_lshlrev_b32_e32 v8, 7, v128
	v_mov_b32_e32 v9, v17
	v_and_b32_e32 v13, 32, v13
	v_lshl_add_u64 v[6:7], v[6:7], 0, v[116:117]
	v_lshl_add_u64 v[8:9], v[2:3], 0, v[8:9]
	v_lshlrev_b32_e32 v118, 1, v13
	v_mov_b32_e32 v119, v17
	v_readlane_b32 s0, v254, 60
	v_lshl_add_u64 v[8:9], v[8:9], 0, v[118:119]
	global_load_dwordx4 v[20:23], v[6:7], off
	global_load_dwordx4 v[28:31], v[8:9], off
	global_load_dwordx4 v[24:27], v[6:7], off offset:16
	global_load_dwordx4 v[32:35], v[8:9], off offset:16
	global_load_dwordx4 v[36:39], v[6:7], off offset:32
	global_load_dwordx4 v[44:47], v[8:9], off offset:32
	global_load_dwordx4 v[40:43], v[6:7], off offset:48
	global_load_dwordx4 v[48:51], v[8:9], off offset:48
	v_lshlrev_b32_e32 v7, 6, v10
	v_lshlrev_b32_e32 v16, 8, v11
	v_or_b32_e32 v11, s0, v11
	s_movk_i32 s0, 0x88
	v_and_b32_e32 v9, 15, v0
	v_bfe_u32 v6, v0, 4, 2
	v_mul_lo_u32 v15, v129, s0
	s_movk_i32 s0, 0x44
	v_lshl_or_b32 v1, v1, 12, v7
	v_bfi_b32 v13, -16, v129, v0
	v_lshlrev_b32_e32 v14, 3, v6
	v_mul_lo_u32 v12, v12, s0
	v_lshlrev_b32_e32 v130, 2, v6
	v_mul_u32_u24_e32 v6, 0x88, v9
	s_movk_i32 s0, 0x4400
	v_mul_lo_u32 v1, v1, s33
	v_med3_i32 v7, v13, 8, 56
	v_add3_u32 v133, v6, v14, s0
	v_add_u32_e32 v6, 0x1800000, v1
	v_lshlrev_b32_e32 v131, 1, v15
	v_add_u32_e32 v15, -8, v7
	v_add_u32_e32 v18, 8, v7
	v_ashrrev_i32_e32 v7, 31, v6
	v_lshl_add_u64 v[6:7], s[30:31], 0, v[6:7]
	v_lshl_add_u64 v[122:123], v[4:5], 0, v[116:117]
	v_lshl_add_u64 v[4:5], v[6:7], 0, v[16:17]
	v_mul_u32_u24_e32 v16, 0x744, v11
	v_lshl_add_u64 v[126:127], s[16:17], 0, v[16:17]
	v_mad_i64_i32 v[120:121], s[0:1], v13, s33, v[4:5]
	v_and_b32_e32 v16, 48, v0
	v_and_b32_e32 v8, 63, v0
	v_lshl_add_u64 v[0:1], v[120:121], 0, v[16:17]
	global_load_dwordx4 v[52:55], v[0:1], off offset:3072
	global_load_dwordx4 v[56:59], v[0:1], off offset:3136
	global_load_dwordx4 v[60:63], v[0:1], off offset:3200
	global_load_dwordx4 v[64:67], v[0:1], off offset:3264
	v_sub_u32_e32 v0, v130, v13
	v_lshl_add_u64 v[124:125], v[2:3], 0, v[118:119]
	v_med3_i32 v119, v0, -15, 15
	v_or_b32_e32 v0, 1, v130
	v_cmp_ge_u32_e64 s[46:47], v0, v15
	v_sub_u32_e32 v0, v0, v13
	v_med3_i32 v135, v0, -15, 15
	v_or_b32_e32 v0, 2, v130
	v_cmp_ge_u32_e64 s[48:49], v0, v15
	v_sub_u32_e32 v0, v0, v13
	v_med3_i32 v136, v0, -15, 15
	v_or_b32_e32 v0, 3, v130
	v_cmp_ge_u32_e64 s[50:51], v0, v15
	v_sub_u32_e32 v0, v0, v13
	s_movk_i32 s0, 0x110
	v_med3_i32 v137, v0, -15, 15
	v_or_b32_e32 v0, 16, v130
	v_mad_u32_u24 v117, v9, s0, v16
	v_cmp_ge_u32_e32 vcc, v0, v15
	v_cmp_lt_u32_e64 s[0:1], v0, v18
	v_sub_u32_e32 v0, v0, v13
	v_med3_i32 v138, v0, -15, 15
	v_or_b32_e32 v0, 17, v130
	s_and_b64 s[64:65], vcc, s[0:1]
	v_cmp_ge_u32_e32 vcc, v0, v15
	v_cmp_lt_u32_e64 s[0:1], v0, v18
	v_sub_u32_e32 v0, v0, v13
	v_med3_i32 v139, v0, -15, 15
	v_or_b32_e32 v0, 18, v130
	s_and_b64 s[66:67], vcc, s[0:1]
	v_cmp_ge_u32_e32 vcc, v0, v15
	v_cmp_lt_u32_e64 s[0:1], v0, v18
	v_sub_u32_e32 v0, v0, v13
	v_med3_i32 v140, v0, -15, 15
	v_or_b32_e32 v0, 19, v130
	s_and_b64 s[68:69], vcc, s[0:1]
	v_cmp_ge_u32_e32 vcc, v0, v15
	v_cmp_lt_u32_e64 s[0:1], v0, v18
	v_sub_u32_e32 v0, v0, v13
	v_med3_i32 v141, v0, -15, 15
	v_or_b32_e32 v0, 32, v130
	s_and_b64 s[70:71], vcc, s[0:1]
	v_cmp_ge_u32_e32 vcc, v0, v15
	v_cmp_lt_u32_e64 s[0:1], v0, v18
	v_sub_u32_e32 v0, v0, v13
	v_med3_i32 v142, v0, -15, 15
	v_or_b32_e32 v0, 33, v130
	s_and_b64 s[72:73], vcc, s[0:1]
	v_cmp_ge_u32_e32 vcc, v0, v15
	v_cmp_lt_u32_e64 s[0:1], v0, v18
	v_sub_u32_e32 v0, v0, v13
	v_med3_i32 v143, v0, -15, 15
	v_or_b32_e32 v0, 34, v130
	s_and_b64 s[74:75], vcc, s[0:1]
	v_cmp_ge_u32_e32 vcc, v0, v15
	v_cmp_lt_u32_e64 s[0:1], v0, v18
	v_sub_u32_e32 v0, v0, v13
	v_med3_i32 v144, v0, -15, 15
	v_or_b32_e32 v0, 35, v130
	s_and_b64 s[76:77], vcc, s[0:1]
	v_cmp_ge_u32_e32 vcc, v0, v15
	v_cmp_lt_u32_e64 s[0:1], v0, v18
	v_sub_u32_e32 v0, v0, v13
	v_med3_i32 v145, v0, -15, 15
	v_or_b32_e32 v0, 48, v130
	v_cmp_lt_u32_e64 s[52:53], v0, v18
	v_sub_u32_e32 v0, v0, v13
	v_med3_i32 v146, v0, -15, 15
	v_or_b32_e32 v0, 49, v130
	v_cmp_lt_u32_e64 s[54:55], v0, v18
	v_sub_u32_e32 v0, v0, v13
	v_med3_i32 v147, v0, -15, 15
	v_or_b32_e32 v0, 50, v130
	v_cmp_lt_u32_e64 s[56:57], v0, v18
	v_sub_u32_e32 v0, v0, v13
	v_med3_i32 v148, v0, -15, 15
	v_or_b32_e32 v0, 51, v130
	v_cmp_lt_u32_e64 s[58:59], v0, v18
	v_mov_b32_e32 v18, v17
	v_mov_b32_e32 v19, v17
	v_sub_u32_e32 v0, v0, v13
	v_mov_b32_e32 v16, v17
	v_mov_b64_e32 v[74:75], v[18:19]
	v_mov_b64_e32 v[82:83], v[18:19]
	v_mov_b64_e32 v[86:87], v[18:19]
	v_mov_b64_e32 v[90:91], v[18:19]
	v_mov_b64_e32 v[94:95], v[18:19]
	v_mov_b64_e32 v[98:99], v[18:19]
	v_mov_b64_e32 v[78:79], v[18:19]
	v_mov_b64_e32 v[70:71], v[18:19]
	v_lshlrev_b32_e32 v132, 1, v12
	v_add3_u32 v12, v194, v131, v116
	v_sub_u32_e32 v134, v128, v10
	s_mov_b32 s83, 0
	v_cmp_eq_u32_e64 s[42:43], 0, v8
	v_cmp_ge_u32_e64 s[44:45], v130, v15
	s_and_b64 s[0:1], vcc, s[0:1]
	v_med3_i32 v149, v0, -15, 15
	v_mov_b32_e32 v151, 0xff800000
	v_mov_b32_e32 v150, 0
	v_mov_b64_e32 v[72:73], v[16:17]
	v_mov_b64_e32 v[80:81], v[16:17]
	v_mov_b64_e32 v[84:85], v[16:17]
	v_mov_b64_e32 v[88:89], v[16:17]
	v_mov_b64_e32 v[92:93], v[16:17]
	v_mov_b64_e32 v[96:97], v[16:17]
	v_mov_b64_e32 v[76:77], v[16:17]
	v_mov_b64_e32 v[68:69], v[16:17]
	s_mov_b32 s34, 0
	v_add3_u32 v14, v194, v132, v118
	s_waitcnt vmcnt(11)
	ds_write_b128 v12, v[20:23]
	s_waitcnt vmcnt(10)
	ds_write_b64 v14, v[28:29] offset:17408
	ds_write_b64 v14, v[30:31] offset:17416
	s_waitcnt vmcnt(9)
	ds_write_b128 v12, v[24:27] offset:16
	s_waitcnt vmcnt(8)
	ds_write_b64 v14, v[32:33] offset:17424
	ds_write_b64 v14, v[34:35] offset:17432
	s_waitcnt vmcnt(7)
	ds_write_b128 v12, v[36:39] offset:32
	s_waitcnt vmcnt(6)
	ds_write_b64 v14, v[44:45] offset:17440
	ds_write_b64 v14, v[46:47] offset:17448
	s_waitcnt vmcnt(5)
	ds_write_b128 v12, v[40:43] offset:48
	s_waitcnt vmcnt(4)
	ds_write_b64 v14, v[48:49] offset:17456
	ds_write_b64 v14, v[50:51] offset:17464
	s_waitcnt lgkmcnt(0)
	s_barrier

.LBB0_390:
	v_cvt_pk_bf16_f32 v0, v0, v1
	v_cvt_pk_bf16_f32 v1, v2, v3
	v_cvt_pk_bf16_f32 v2, v4, v5
	v_cvt_pk_bf16_f32 v3, v6, v7
	v_cvt_pk_bf16_f32 v4, v8, v9
	v_cvt_pk_bf16_f32 v5, v10, v11
	v_cvt_pk_bf16_f32 v6, v12, v13
	v_add_u32_e32 v12, v133, v18
	ds_read2_b64 v[8:11], v12 offset1:4
	ds_read2_b64 v[100:103], v12 offset0:8 offset1:12
	v_add_u32_e32 v13, 0x880, v12
	ds_read2_b64 v[104:107], v13 offset1:4
	ds_read2_b64 v[108:111], v13 offset0:8 offset1:12
	v_exp_f32_e32 v15, v15
	s_waitcnt lgkmcnt(3)
	v_add_u32_e32 v13, 0x1100, v12
	v_mfma_f32_16x16x32_bf16 v[8:11], v[8:11], v[0:3], v[96:99]
	ds_read2_b64 v[112:115], v13 offset1:4
	v_cvt_pk_bf16_f32 v7, v14, v15
	s_waitcnt lgkmcnt(3)
	s_andn2_b64 vcc, exec, s[78:79]
	s_nop 0
	v_mfma_f32_16x16x32_bf16 v[96:99], v[100:103], v[4:7], v[8:11]
	ds_read2_b64 v[8:11], v13 offset0:8 offset1:12
	s_waitcnt lgkmcnt(3)
	v_add_u32_e32 v13, 0x1980, v12
	ds_read2_b64 v[100:103], v13 offset1:4
	v_mfma_f32_16x16x32_bf16 v[92:95], v[104:107], v[0:3], v[92:95]
	s_waitcnt lgkmcnt(3)
	ds_read2_b64 v[104:107], v13 offset0:8 offset1:12
	s_waitcnt lgkmcnt(3)
	v_add_u32_e32 v13, 0x2200, v12
	v_mfma_f32_16x16x32_bf16 v[88:91], v[112:115], v[0:3], v[88:91]
	v_mfma_f32_16x16x32_bf16 v[92:95], v[108:111], v[4:7], v[92:95]
	ds_read2_b64 v[108:111], v13 offset1:4
	s_waitcnt lgkmcnt(3)
	s_nop 0
	v_mfma_f32_16x16x32_bf16 v[88:91], v[8:11], v[4:7], v[88:91]
	ds_read2_b64 v[8:11], v13 offset0:8 offset1:12
	s_waitcnt lgkmcnt(3)
	v_add_u32_e32 v13, 0x2a80, v12
	v_mfma_f32_16x16x32_bf16 v[84:87], v[100:103], v[0:3], v[84:87]
	ds_read2_b64 v[100:103], v13 offset1:4
	s_waitcnt lgkmcnt(3)
	s_nop 0
	v_mfma_f32_16x16x32_bf16 v[84:87], v[104:107], v[4:7], v[84:87]
	ds_read2_b64 v[104:107], v13 offset0:8 offset1:12
	s_waitcnt lgkmcnt(3)
	v_add_u32_e32 v13, 0x3300, v12
	v_mfma_f32_16x16x32_bf16 v[80:83], v[108:111], v[0:3], v[80:83]
	ds_read2_b64 v[108:111], v13 offset1:4
	s_waitcnt lgkmcnt(3)
	v_add_u32_e32 v12, 0x3b80, v12
	v_mfma_f32_16x16x32_bf16 v[80:83], v[8:11], v[4:7], v[80:83]
	ds_read2_b64 v[8:11], v13 offset0:8 offset1:12
	s_waitcnt lgkmcnt(3)
	s_nop 0
	v_mfma_f32_16x16x32_bf16 v[72:75], v[100:103], v[0:3], v[72:75]
	ds_read2_b64 v[100:103], v12 offset1:4
	s_waitcnt lgkmcnt(3)
	s_nop 0
	v_mfma_f32_16x16x32_bf16 v[72:75], v[104:107], v[4:7], v[72:75]
	ds_read2_b64 v[104:107], v12 offset0:8 offset1:12
	s_waitcnt lgkmcnt(3)
	s_waitcnt lgkmcnt(2)
	s_waitcnt lgkmcnt(1)
	s_nop 0
	v_mfma_f32_16x16x32_bf16 v[76:79], v[108:111], v[0:3], v[76:79]
	s_waitcnt lgkmcnt(0)
	v_mfma_f32_16x16x32_bf16 v[0:3], v[100:103], v[0:3], v[68:71]
	v_mfma_f32_16x16x32_bf16 v[76:79], v[8:11], v[4:7], v[76:79]
	v_mfma_f32_16x16x32_bf16 v[68:71], v[104:107], v[4:7], v[0:3]
	s_cbranch_vccnz .LBB0_392
	s_bitcmp1_b32 s82, 0
	s_cselect_b32 s40, 0x8c00, 0
	s_nop 2
	v_add_u32_e32 v0, s40, v194
	v_add3_u32 v1, v0, v131, v116
	v_add3_u32 v0, v0, v132, v118
	ds_write_b128 v1, v[20:23]
	ds_write_b64 v0, v[28:29] offset:17408
	ds_write_b64 v0, v[30:31] offset:17416
	ds_write_b128 v1, v[24:27] offset:16
	ds_write_b64 v0, v[32:33] offset:17424
	ds_write_b64 v0, v[34:35] offset:17432
	ds_write_b128 v1, v[36:39] offset:32
	ds_write_b64 v0, v[44:45] offset:17440
	ds_write_b64 v0, v[46:47] offset:17448
	ds_write_b128 v1, v[40:43] offset:48
	ds_write_b64 v0, v[48:49] offset:17456
	ds_write_b64 v0, v[50:51] offset:17464

.LBB0_770:
	s_movk_i32 s25, 0x480
	v_cmp_gt_u32_e32 vcc, s25, v5
	s_mov_b64 s[42:43], 0
	s_and_saveexec_b64 s[46:47], vcc
	s_cbranch_execz .LBB0_789
	v_mov_b32_e32 v0, v217
	s_nop 0
	v_cmp_eq_u32_e32 vcc, 0, v0
	s_and_saveexec_b64 s[42:43], vcc
	ds_write_b32 v227, v17
	s_or_b64 exec, exec, s[42:43]
	v_add_u32_e32 v1, 0xfffffc00, v5
	v_lshrrev_b32_e32 v1, 3, v1
	s_waitcnt vmcnt(1)
	v_bfe_u32 v2, v4, 1, 1
	v_lshl_or_b32 v16, v1, 1, v2
	v_readlane_b32 s42, v254, 31
	v_lshlrev_b64 v[2:3], 16, v[16:17]
	v_readlane_b32 s43, v254, 32
	v_lshlrev_b32_e32 v14, 5, v0
	v_ashrrev_i32_e32 v8, 1, v0
	v_lshl_add_u64 v[6:7], s[42:43], 0, v[2:3]
	v_readlane_b32 s42, v254, 29
	v_and_b32_e32 v9, 0x60, v14
	v_readlane_b32 s43, v254, 30
	v_lshlrev_b32_e32 v166, 1, v9
	v_ashrrev_i32_e32 v9, 31, v8
	v_lshl_add_u64 v[2:3], s[42:43], 0, v[2:3]
	v_lshlrev_b64 v[12:13], 9, v[8:9]
	v_and_b32_e32 v9, 32, v14
	v_lshl_add_u64 v[2:3], v[2:3], 0, v[12:13]
	v_lshlrev_b32_e32 v170, 1, v9
	v_mov_b32_e32 v171, v17
	v_lshl_add_u64 v[172:173], v[2:3], 0, v[170:171]
	v_lshlrev_b32_e32 v2, 5, v5
	v_and_b32_e32 v2, 0x80, v2
	v_and_b32_e32 v4, 3, v4
	v_lshl_or_b32 v1, v1, 8, v2
	v_mov_b64_e32 v[2:3], s[30:31]
	v_ashrrev_i32_e32 v164, 2, v0
	v_mad_u64_u32 v[2:3], s[42:43], v1, s33, v[2:3]
	v_lshlrev_b32_e32 v4, 8, v4
	v_mov_b32_e32 v5, v17
	v_ashrrev_i32_e32 v165, 31, v164
	v_lshl_add_u64 v[2:3], v[2:3], 0, v[4:5]
	s_mov_b64 s[42:43], 0x1000
	v_lshlrev_b64 v[10:11], 8, v[164:165]
	v_lshl_add_u64 v[174:175], v[2:3], 0, s[42:43]
	v_and_b32_e32 v1, 15, v0
	s_movk_i32 s25, 0xffe0
	v_and_b32_e32 v16, 48, v0
	v_lshl_add_u64 v[10:11], v[6:7], 0, v[10:11]
	v_mov_b32_e32 v167, v17
	v_and_or_b32 v9, v8, s25, v1
	v_lshl_add_u64 v[2:3], v[174:175], 0, v[16:17]
	v_lshl_add_u64 v[10:11], v[10:11], 0, v[166:167]
	v_mad_i64_i32 v[4:5], s[42:43], v9, s33, v[2:3]
	global_load_dwordx4 v[20:23], v[10:11], off
	global_load_dwordx4 v[36:39], v[172:173], off
	global_load_dwordx4 v[32:35], v[10:11], off offset:16
	global_load_dwordx4 v[40:43], v[172:173], off offset:16
	global_load_dwordx4 v[44:47], v[10:11], off offset:32
	global_load_dwordx4 v[56:59], v[172:173], off offset:32
	global_load_dwordx4 v[52:55], v[10:11], off offset:48
	global_load_dwordx4 v[72:75], v[172:173], off offset:48
	global_load_dwordx4 v[60:63], v[4:5], off
	global_load_dwordx4 v[64:67], v[4:5], off offset:64
	global_load_dwordx4 v[68:71], v[4:5], off offset:128
	global_load_dwordx4 v[76:79], v[4:5], off offset:192
	v_or_b32_e32 v4, 16, v9
	v_mad_i64_i32 v[2:3], s[42:43], v4, s33, v[2:3]
	global_load_dwordx4 v[80:83], v[2:3], off
	global_load_dwordx4 v[88:91], v[2:3], off offset:64
	global_load_dwordx4 v[92:95], v[2:3], off offset:128
	global_load_dwordx4 v[96:99], v[2:3], off offset:192
	v_and_b32_e32 v2, 63, v0
	v_bfe_u32 v0, v0, 4, 2
	s_movk_i32 s25, 0x88
	v_lshlrev_b32_e32 v176, 3, v0
	v_mul_lo_u32 v0, v164, s25
	s_movk_i32 s25, 0x44
	v_mul_lo_u32 v3, v8, s25
	v_mul_u32_u24_e32 v5, 0x88, v1
	s_movk_i32 s25, 0x4400
	v_lshlrev_b32_e32 v165, 1, v0
	v_lshlrev_b32_e32 v171, 1, v3
	v_add3_u32 v177, v5, v176, s25
	s_movk_i32 s25, 0x110
	v_mad_i64_i32 v[178:179], s[42:43], v9, s33, 0
	v_mad_i64_i32 v[168:169], s[42:43], v4, s33, 0
	v_add3_u32 v0, v194, v165, v166
	v_add3_u32 v3, v194, v171, v170
	v_mad_u32_u24 v182, v1, s25, v16
	v_mov_b32_e32 v16, v17
	v_mov_b32_e32 v18, v17
	v_mov_b32_e32 v19, v17
	v_lshl_add_u64 v[180:181], v[6:7], 0, v[166:167]
	v_cmp_eq_u32_e64 s[42:43], 0, v2
	v_mov_b64_e32 v[102:103], v[18:19]
	v_mov_b64_e32 v[4:5], v[16:17]
	v_mov_b64_e32 v[106:107], v[18:19]
	v_mov_b64_e32 v[8:9], v[16:17]
	v_mov_b64_e32 v[114:115], v[18:19]
	v_mov_b64_e32 v[30:31], v[18:19]
	v_mov_b64_e32 v[122:123], v[18:19]
	v_mov_b64_e32 v[50:51], v[18:19]
	v_mov_b64_e32 v[126:127], v[18:19]
	v_mov_b64_e32 v[86:87], v[18:19]
	s_waitcnt vmcnt(15)
	ds_write_b128 v0, v[20:23]
	s_waitcnt vmcnt(14)
	ds_write_b64 v3, v[36:37] offset:17408
	ds_write_b64 v3, v[38:39] offset:17416
	s_waitcnt vmcnt(13)
	ds_write_b128 v0, v[32:35] offset:16
	s_waitcnt vmcnt(12)
	ds_write_b64 v3, v[40:41] offset:17424
	ds_write_b64 v3, v[42:43] offset:17432
	s_waitcnt vmcnt(11)
	ds_write_b128 v0, v[44:47] offset:32
	s_waitcnt vmcnt(10)
	ds_write_b64 v3, v[56:57] offset:17440
	ds_write_b64 v3, v[58:59] offset:17448
	s_waitcnt vmcnt(9)
	ds_write_b128 v0, v[52:55] offset:48
	s_waitcnt vmcnt(8)
	ds_write_b64 v3, v[72:73] offset:17456
	ds_write_b64 v3, v[74:75] offset:17464
	v_mov_b64_e32 v[0:1], v[16:17]
	v_mov_b64_e32 v[130:131], v[18:19]
	v_mov_b64_e32 v[118:119], v[18:19]
	v_mov_b64_e32 v[12:13], v[16:17]
	v_mov_b64_e32 v[110:111], v[18:19]
	v_mov_b64_e32 v[26:27], v[18:19]
	s_mov_b32 s50, 0
	v_mov_b32_e32 v167, 0
	v_mov_b32_e32 v187, 0xff800000
	v_mov_b64_e32 v[2:3], v[18:19]
	v_mov_b64_e32 v[100:101], v[16:17]
	v_mov_b64_e32 v[6:7], v[18:19]
	v_mov_b64_e32 v[104:105], v[16:17]
	v_mov_b64_e32 v[10:11], v[18:19]
	v_mov_b64_e32 v[112:113], v[16:17]
	v_mov_b64_e32 v[28:29], v[16:17]
	v_mov_b64_e32 v[120:121], v[16:17]
	v_mov_b64_e32 v[48:49], v[16:17]
	v_mov_b64_e32 v[124:125], v[16:17]
	v_mov_b64_e32 v[84:85], v[16:17]
	v_mov_b64_e32 v[128:129], v[16:17]
	v_mov_b32_e32 v188, 0xff800000
	v_mov_b32_e32 v183, 0
	v_mov_b64_e32 v[116:117], v[16:17]
	v_mov_b64_e32 v[14:15], v[18:19]
	v_mov_b64_e32 v[108:109], v[16:17]
	v_mov_b64_e32 v[24:25], v[16:17]
	s_mov_b32 s25, 0
	s_waitcnt lgkmcnt(0)
	s_barrier

.LBB0_780:
	v_fma_f32 v148, v148, s94, -v188
	v_fma_f32 v149, v149, s94, -v188
	v_fma_f32 v150, v150, s94, -v188
	v_fma_f32 v151, v151, s94, -v188
	v_fma_f32 v152, v152, s94, -v188
	v_fma_f32 v153, v153, s94, -v188
	v_fma_f32 v154, v154, s94, -v188
	v_fma_f32 v155, v155, s94, -v188
	v_fma_f32 v132, v132, s94, -v185
	v_fma_f32 v133, v133, s94, -v185
	v_fma_f32 v134, v134, s94, -v185
	v_fma_f32 v135, v135, s94, -v185
	v_fma_f32 v136, v136, s94, -v185
	v_fma_f32 v137, v137, s94, -v185
	v_fma_f32 v138, v138, s94, -v185
	v_fma_f32 v139, v139, s94, -v185
	v_exp_f32_e32 v148, v148
	v_exp_f32_e32 v149, v149
	v_exp_f32_e32 v150, v150
	v_exp_f32_e32 v151, v151
	v_exp_f32_e32 v152, v152
	v_exp_f32_e32 v153, v153
	v_exp_f32_e32 v154, v154
	v_exp_f32_e32 v155, v155
	v_exp_f32_e32 v132, v132
	v_exp_f32_e32 v133, v133
	v_exp_f32_e32 v134, v134
	v_exp_f32_e32 v135, v135
	v_exp_f32_e32 v136, v136
	v_exp_f32_e32 v137, v137
	v_exp_f32_e32 v138, v138
	v_exp_f32_e32 v139, v139
	v_add_u32_e32 v186, v177, v186
	ds_read2_b64 v[210:213], v186 offset1:4
	ds_read2_b64 v[232:235], v186 offset0:8 offset1:12
	v_fma_f32 v156, v156, s94, -v188
	v_fma_f32 v157, v157, s94, -v188
	v_fma_f32 v158, v158, s94, -v188
	v_fma_f32 v159, v159, s94, -v188
	v_fma_f32 v160, v160, s94, -v188
	v_fma_f32 v161, v161, s94, -v188
	v_fma_f32 v162, v162, s94, -v188
	v_fma_f32 v163, v163, s94, -v188
	v_fma_f32 v140, v140, s94, -v185
	v_fma_f32 v141, v141, s94, -v185
	v_fma_f32 v142, v142, s94, -v185
	v_fma_f32 v143, v143, s94, -v185
	v_fma_f32 v144, v144, s94, -v185
	v_fma_f32 v145, v145, s94, -v185
	v_fma_f32 v146, v146, s94, -v185
	v_fma_f32 v147, v147, s94, -v185
	v_add_u32_e32 v187, 0x880, v186
	ds_read2_b64 v[238:241], v187 offset1:4
	v_exp_f32_e32 v156, v156
	v_exp_f32_e32 v157, v157
	v_exp_f32_e32 v158, v158
	v_exp_f32_e32 v159, v159
	v_exp_f32_e32 v160, v160
	v_exp_f32_e32 v161, v161
	v_exp_f32_e32 v162, v162
	v_exp_f32_e32 v163, v163
	v_exp_f32_e32 v140, v140
	v_exp_f32_e32 v141, v141
	v_exp_f32_e32 v142, v142
	v_exp_f32_e32 v143, v143
	v_exp_f32_e32 v144, v144
	v_exp_f32_e32 v145, v145
	v_exp_f32_e32 v146, v146
	v_exp_f32_e32 v147, v147
	v_cvt_pk_bf16_f32 v190, v132, v133
	v_cvt_pk_bf16_f32 v191, v134, v135
	v_cvt_pk_bf16_f32 v192, v136, v137
	v_cvt_pk_bf16_f32 v193, v138, v139
	v_cvt_pk_bf16_f32 v202, v148, v149
	v_cvt_pk_bf16_f32 v203, v150, v151
	v_cvt_pk_bf16_f32 v204, v152, v153
	v_cvt_pk_bf16_f32 v205, v154, v155
	ds_read2_b64 v[242:245], v187 offset0:8 offset1:12
	s_waitcnt lgkmcnt(3)
	v_add_u32_e32 v187, 0x1100, v186
	v_mfma_f32_16x16x32_bf16 v[128:131], v[210:213], v[190:193], v[128:131]
	v_cvt_pk_bf16_f32 v206, v140, v141
	v_cvt_pk_bf16_f32 v207, v142, v143
	v_cvt_pk_bf16_f32 v208, v144, v145
	v_mfma_f32_16x16x32_bf16 v[84:87], v[210:213], v[202:205], v[84:87]
	ds_read2_b64 v[210:213], v187 offset1:4
	v_cvt_pk_bf16_f32 v209, v146, v147
	v_cvt_pk_bf16_f32 v246, v156, v157
	s_waitcnt lgkmcnt(3)
	v_cvt_pk_bf16_f32 v247, v158, v159
	v_cvt_pk_bf16_f32 v248, v160, v161
	v_cvt_pk_bf16_f32 v249, v162, v163
	v_mfma_f32_16x16x32_bf16 v[128:131], v[232:235], v[206:209], v[128:131]
	s_andn2_b64 vcc, exec, s[48:49]
	v_mfma_f32_16x16x32_bf16 v[84:87], v[232:235], v[246:249], v[84:87]
	ds_read2_b64 v[232:235], v187 offset0:8 offset1:12
	s_waitcnt lgkmcnt(3)
	v_add_u32_e32 v187, 0x1980, v186
	v_mfma_f32_16x16x32_bf16 v[124:127], v[238:241], v[190:193], v[124:127]
	v_mfma_f32_16x16x32_bf16 v[48:51], v[238:241], v[202:205], v[48:51]
	ds_read2_b64 v[238:241], v187 offset1:4
	s_waitcnt lgkmcnt(3)
	s_nop 0
	v_mfma_f32_16x16x32_bf16 v[124:127], v[242:245], v[206:209], v[124:127]
	v_mfma_f32_16x16x32_bf16 v[48:51], v[242:245], v[246:249], v[48:51]
	ds_read2_b64 v[242:245], v187 offset0:8 offset1:12
	s_waitcnt lgkmcnt(3)
	v_add_u32_e32 v187, 0x2200, v186
	v_mfma_f32_16x16x32_bf16 v[120:123], v[210:213], v[190:193], v[120:123]
	v_mfma_f32_16x16x32_bf16 v[28:31], v[210:213], v[202:205], v[28:31]
	ds_read2_b64 v[210:213], v187 offset1:4
	s_waitcnt lgkmcnt(3)
	s_nop 0
	v_mfma_f32_16x16x32_bf16 v[120:123], v[232:235], v[206:209], v[120:123]
	v_mfma_f32_16x16x32_bf16 v[28:31], v[232:235], v[246:249], v[28:31]
	ds_read2_b64 v[232:235], v187 offset0:8 offset1:12
	s_waitcnt lgkmcnt(3)
	v_add_u32_e32 v187, 0x2a80, v186
	v_mfma_f32_16x16x32_bf16 v[112:115], v[238:241], v[190:193], v[112:115]
	v_mfma_f32_16x16x32_bf16 v[8:11], v[238:241], v[202:205], v[8:11]
	ds_read2_b64 v[238:241], v187 offset1:4
	s_waitcnt lgkmcnt(3)
	s_nop 0
	v_mfma_f32_16x16x32_bf16 v[112:115], v[242:245], v[206:209], v[112:115]
	v_mfma_f32_16x16x32_bf16 v[8:11], v[242:245], v[246:249], v[8:11]
	ds_read2_b64 v[242:245], v187 offset0:8 offset1:12
	s_waitcnt lgkmcnt(3)
	v_add_u32_e32 v187, 0x3300, v186
	v_mfma_f32_16x16x32_bf16 v[104:107], v[210:213], v[190:193], v[104:107]
	v_add_u32_e32 v186, 0x3b80, v186
	v_mfma_f32_16x16x32_bf16 v[4:7], v[210:213], v[202:205], v[4:7]
	ds_read2_b64 v[210:213], v187 offset1:4
	s_waitcnt lgkmcnt(3)
	s_nop 0
	v_mfma_f32_16x16x32_bf16 v[104:107], v[232:235], v[206:209], v[104:107]
	v_mfma_f32_16x16x32_bf16 v[4:7], v[232:235], v[246:249], v[4:7]
	ds_read2_b64 v[232:235], v187 offset0:8 offset1:12
	s_waitcnt lgkmcnt(3)
	s_nop 0
	v_mfma_f32_16x16x32_bf16 v[100:103], v[238:241], v[190:193], v[100:103]
	v_mfma_f32_16x16x32_bf16 v[0:3], v[238:241], v[202:205], v[0:3]
	ds_read2_b64 v[238:241], v186 offset1:4
	s_waitcnt lgkmcnt(3)
	s_nop 0
	v_mfma_f32_16x16x32_bf16 v[100:103], v[242:245], v[206:209], v[100:103]
	v_mfma_f32_16x16x32_bf16 v[0:3], v[242:245], v[246:249], v[0:3]
	ds_read2_b64 v[242:245], v186 offset0:8 offset1:12
	s_waitcnt lgkmcnt(3)
	s_waitcnt lgkmcnt(2)
	s_waitcnt lgkmcnt(1)
	s_nop 0
	v_mfma_f32_16x16x32_bf16 v[116:119], v[210:213], v[190:193], v[116:119]
	s_waitcnt lgkmcnt(0)
	v_mfma_f32_16x16x32_bf16 v[12:15], v[210:213], v[202:205], v[12:15]
	v_mfma_f32_16x16x32_bf16 v[108:111], v[238:241], v[190:193], v[108:111]
	v_mfma_f32_16x16x32_bf16 v[24:27], v[238:241], v[202:205], v[24:27]
	v_mfma_f32_16x16x32_bf16 v[116:119], v[232:235], v[206:209], v[116:119]
	v_mfma_f32_16x16x32_bf16 v[12:15], v[232:235], v[246:249], v[12:15]
	v_mfma_f32_16x16x32_bf16 v[108:111], v[242:245], v[206:209], v[108:111]
	v_mfma_f32_16x16x32_bf16 v[24:27], v[242:245], v[246:249], v[24:27]
	s_cbranch_vccnz .LBB0_782
	s_bitcmp1_b32 s52, 0
	s_cselect_b32 s34, 0x8c00, 0
	v_add_u32_e32 v186, s34, v194
	v_add3_u32 v187, v186, v165, v166
	v_add3_u32 v186, v186, v171, v170
	ds_write_b128 v187, v[20:23]
	ds_write_b64 v186, v[36:37] offset:17408
	ds_write_b64 v186, v[38:39] offset:17416
	ds_write_b128 v187, v[32:35] offset:16
	ds_write_b64 v186, v[40:41] offset:17424
	ds_write_b64 v186, v[42:43] offset:17432
	ds_write_b128 v187, v[44:47] offset:32
	ds_write_b64 v186, v[56:57] offset:17440
	ds_write_b64 v186, v[58:59] offset:17448
	ds_write_b128 v187, v[52:55] offset:48
	ds_write_b64 v186, v[72:73] offset:17456
	ds_write_b64 v186, v[74:75] offset:17464

.LBB0_790:
	v_mov_b32_e32 v0, v217
	s_nop 0
	v_cmp_eq_u32_e32 vcc, 0, v0
	s_and_saveexec_b64 s[42:43], vcc
	ds_write_b32 v227, v17
	s_or_b64 exec, exec, s[42:43]
	v_ashrrev_i32_e32 v1, 7, v5
	s_waitcnt vmcnt(1)
	v_bfe_u32 v2, v4, 1, 1
	v_lshl_or_b32 v2, v1, 1, v2
	s_mov_b32 s25, 0x90000
	v_mul_lo_u32 v2, v2, s25
	v_ashrrev_i32_e32 v3, 31, v2
	v_mov_b64_e32 v[6:7], 0x200000
	v_readlane_b32 s42, v254, 31
	v_lshl_add_u64 v[2:3], v[2:3], 1, v[6:7]
	v_readlane_b32 s43, v254, 32
	v_lshlrev_b32_e32 v5, 5, v0
	v_ashrrev_i32_e32 v10, 1, v0
	v_lshl_add_u64 v[6:7], s[42:43], 0, v[2:3]
	v_readlane_b32 s42, v254, 29
	v_readlane_b32 s43, v254, 30
	v_and_b32_e32 v11, 0x60, v5
	s_movk_i32 s25, 0x2400
	v_lshl_add_u64 v[2:3], s[42:43], 0, v[2:3]
	v_and_b32_e32 v5, 32, v5
	v_mad_i64_i32 v[2:3], s[42:43], v10, s25, v[2:3]
	v_lshlrev_b32_e32 v170, 1, v5
	v_mov_b32_e32 v171, v17
	v_lshl_add_u64 v[172:173], v[2:3], 0, v[170:171]
	v_lshlrev_b32_e32 v2, 5, v4
	v_and_b32_e32 v2, 0xf80, v2
	v_lshl_or_b32 v1, v1, 12, v2
	v_mul_lo_u32 v1, v1, s33
	v_ashrrev_i32_e32 v166, 2, v0
	v_add_u32_e32 v2, 0x1800000, v1
	v_ashrrev_i32_e32 v167, 31, v166
	v_and_b32_e32 v5, 3, v4
	v_ashrrev_i32_e32 v3, 31, v2
	v_lshlrev_b64 v[8:9], 8, v[166:167]
	v_lshl_add_u64 v[2:3], s[30:31], 0, v[2:3]
	v_lshlrev_b32_e32 v16, 8, v5
	v_lshl_add_u64 v[8:9], v[6:7], 0, v[8:9]
	v_lshlrev_b32_e32 v168, 1, v11
	v_mov_b32_e32 v169, v17
	v_lshl_add_u64 v[2:3], v[2:3], 0, v[16:17]
	s_mov_b64 s[42:43], 0x1000
	v_lshl_add_u64 v[8:9], v[8:9], 0, v[168:169]
	v_lshl_add_u64 v[174:175], v[2:3], 0, s[42:43]
	v_and_b32_e32 v1, 15, v0
	s_movk_i32 s25, 0xffe0
	v_and_b32_e32 v16, 48, v0
	global_load_dwordx4 v[44:47], v[8:9], off
	global_load_dwordx4 v[52:55], v[172:173], off
	global_load_dwordx4 v[48:51], v[8:9], off offset:16
	global_load_dwordx4 v[60:63], v[172:173], off offset:16
	global_load_dwordx4 v[64:67], v[8:9], off offset:32
	global_load_dwordx4 v[72:75], v[172:173], off offset:32
	global_load_dwordx4 v[68:71], v[8:9], off offset:48
	global_load_dwordx4 v[88:91], v[172:173], off offset:48
	v_and_or_b32 v8, v10, s25, v1
	v_lshl_add_u64 v[2:3], v[174:175], 0, v[16:17]
	v_mad_i64_i32 v[4:5], s[42:43], v8, s33, v[2:3]
	global_load_dwordx4 v[76:79], v[4:5], off
	global_load_dwordx4 v[84:87], v[4:5], off offset:64
	global_load_dwordx4 v[92:95], v[4:5], off offset:128
	global_load_dwordx4 v[96:99], v[4:5], off offset:192
	v_or_b32_e32 v4, 16, v8
	v_mad_i64_i32 v[2:3], s[42:43], v4, s33, v[2:3]
	global_load_dwordx4 v[100:103], v[2:3], off
	global_load_dwordx4 v[104:107], v[2:3], off offset:64
	global_load_dwordx4 v[108:111], v[2:3], off offset:128
	global_load_dwordx4 v[112:115], v[2:3], off offset:192
	v_and_b32_e32 v2, 63, v0
	v_bfe_u32 v0, v0, 4, 2
	s_movk_i32 s25, 0x88
	v_lshlrev_b32_e32 v178, 3, v0
	v_mul_lo_u32 v0, v166, s25
	s_movk_i32 s25, 0x44
	v_mul_lo_u32 v3, v10, s25
	v_mul_u32_u24_e32 v5, 0x88, v1
	s_movk_i32 s25, 0x4400
	v_lshlrev_b32_e32 v167, 1, v0
	v_lshlrev_b32_e32 v171, 1, v3
	v_add3_u32 v179, v5, v178, s25
	s_movk_i32 s25, 0x110
	v_mad_i64_i32 v[176:177], s[42:43], v8, s33, 0
	v_mad_i64_i32 v[164:165], s[42:43], v4, s33, 0
	v_add3_u32 v0, v194, v167, v168
	v_add3_u32 v3, v194, v171, v170
	v_lshl_add_u64 v[180:181], v[6:7], 0, v[168:169]
	v_mad_u32_u24 v169, v1, s25, v16
	v_mov_b32_e32 v16, v17
	v_mov_b32_e32 v18, v17
	v_mov_b32_e32 v19, v17
	v_cmp_eq_u32_e64 s[42:43], 0, v2
	v_mov_b64_e32 v[58:59], v[18:19]
	v_mov_b64_e32 v[8:9], v[16:17]
	v_mov_b64_e32 v[82:83], v[18:19]
	v_mov_b64_e32 v[22:23], v[18:19]
	v_mov_b64_e32 v[118:119], v[18:19]
	v_mov_b64_e32 v[26:27], v[18:19]
	v_mov_b64_e32 v[122:123], v[18:19]
	v_mov_b64_e32 v[30:31], v[18:19]
	s_waitcnt vmcnt(15)
	ds_write_b128 v0, v[44:47]
	s_waitcnt vmcnt(14)
	ds_write_b64 v3, v[52:53] offset:17408
	ds_write_b64 v3, v[54:55] offset:17416
	s_waitcnt vmcnt(13)
	ds_write_b128 v0, v[48:51] offset:16
	s_waitcnt vmcnt(12)
	ds_write_b64 v3, v[60:61] offset:17424
	ds_write_b64 v3, v[62:63] offset:17432
	s_waitcnt vmcnt(11)
	ds_write_b128 v0, v[64:67] offset:32
	s_waitcnt vmcnt(10)
	ds_write_b64 v3, v[72:73] offset:17440
	ds_write_b64 v3, v[74:75] offset:17448
	s_waitcnt vmcnt(9)
	ds_write_b128 v0, v[68:71] offset:48
	s_waitcnt vmcnt(8)
	ds_write_b64 v3, v[88:89] offset:17456
	ds_write_b64 v3, v[90:91] offset:17464
	v_mov_b64_e32 v[0:1], v[16:17]
	v_mov_b64_e32 v[126:127], v[18:19]
	v_mov_b64_e32 v[34:35], v[18:19]
	v_mov_b64_e32 v[130:131], v[18:19]
	v_mov_b64_e32 v[42:43], v[18:19]
	v_mov_b64_e32 v[12:13], v[16:17]
	v_mov_b64_e32 v[38:39], v[18:19]
	v_mov_b64_e32 v[4:5], v[16:17]
	s_mov_b32 s50, 0
	v_mov_b32_e32 v182, 0
	v_mov_b32_e32 v187, 0xff800000
	v_mov_b64_e32 v[2:3], v[18:19]
	v_mov_b64_e32 v[56:57], v[16:17]
	v_mov_b64_e32 v[10:11], v[18:19]
	v_mov_b64_e32 v[80:81], v[16:17]
	v_mov_b64_e32 v[20:21], v[16:17]
	v_mov_b64_e32 v[116:117], v[16:17]
	v_mov_b64_e32 v[24:25], v[16:17]
	v_mov_b64_e32 v[120:121], v[16:17]
	v_mov_b64_e32 v[28:29], v[16:17]
	v_mov_b64_e32 v[124:125], v[16:17]
	v_mov_b64_e32 v[32:33], v[16:17]
	v_mov_b64_e32 v[128:129], v[16:17]
	v_mov_b32_e32 v188, 0xff800000
	v_mov_b32_e32 v183, 0
	v_mov_b64_e32 v[40:41], v[16:17]
	v_mov_b64_e32 v[14:15], v[18:19]
	v_mov_b64_e32 v[36:37], v[16:17]
	v_mov_b64_e32 v[6:7], v[18:19]
	s_mov_b32 s25, 0
	s_waitcnt lgkmcnt(0)
	s_barrier

.LBB0_799:
	v_fma_f32 v148, v148, s94, -v188
	v_fma_f32 v149, v149, s94, -v188
	v_fma_f32 v150, v150, s94, -v188
	v_fma_f32 v151, v151, s94, -v188
	v_fma_f32 v152, v152, s94, -v188
	v_fma_f32 v153, v153, s94, -v188
	v_fma_f32 v154, v154, s94, -v188
	v_fma_f32 v155, v155, s94, -v188
	v_fma_f32 v132, v132, s94, -v185
	v_fma_f32 v133, v133, s94, -v185
	v_fma_f32 v134, v134, s94, -v185
	v_fma_f32 v135, v135, s94, -v185
	v_fma_f32 v136, v136, s94, -v185
	v_fma_f32 v137, v137, s94, -v185
	v_fma_f32 v138, v138, s94, -v185
	v_fma_f32 v139, v139, s94, -v185
	v_exp_f32_e32 v148, v148
	v_exp_f32_e32 v149, v149
	v_exp_f32_e32 v150, v150
	v_exp_f32_e32 v151, v151
	v_exp_f32_e32 v152, v152
	v_exp_f32_e32 v153, v153
	v_exp_f32_e32 v154, v154
	v_exp_f32_e32 v155, v155
	v_exp_f32_e32 v132, v132
	v_exp_f32_e32 v133, v133
	v_exp_f32_e32 v134, v134
	v_exp_f32_e32 v135, v135
	v_exp_f32_e32 v136, v136
	v_exp_f32_e32 v137, v137
	v_exp_f32_e32 v138, v138
	v_exp_f32_e32 v139, v139
	v_add_u32_e32 v186, v179, v186
	ds_read2_b64 v[238:241], v186 offset1:4
	ds_read2_b64 v[242:245], v186 offset0:8 offset1:12
	v_fma_f32 v156, v156, s94, -v188
	v_fma_f32 v157, v157, s94, -v188
	v_fma_f32 v158, v158, s94, -v188
	v_fma_f32 v159, v159, s94, -v188
	v_fma_f32 v160, v160, s94, -v188
	v_fma_f32 v161, v161, s94, -v188
	v_fma_f32 v162, v162, s94, -v188
	v_fma_f32 v163, v163, s94, -v188
	v_fma_f32 v140, v140, s94, -v185
	v_fma_f32 v141, v141, s94, -v185
	v_fma_f32 v142, v142, s94, -v185
	v_fma_f32 v143, v143, s94, -v185
	v_fma_f32 v144, v144, s94, -v185
	v_fma_f32 v145, v145, s94, -v185
	v_fma_f32 v146, v146, s94, -v185
	v_fma_f32 v147, v147, s94, -v185
	v_add_u32_e32 v187, 0x880, v186
	ds_read2_b64 v[246:249], v187 offset1:4
	v_exp_f32_e32 v156, v156
	v_exp_f32_e32 v157, v157
	v_exp_f32_e32 v158, v158
	v_exp_f32_e32 v159, v159
	v_exp_f32_e32 v160, v160
	v_exp_f32_e32 v161, v161
	v_exp_f32_e32 v162, v162
	v_exp_f32_e32 v163, v163
	v_exp_f32_e32 v140, v140
	v_exp_f32_e32 v141, v141
	v_exp_f32_e32 v142, v142
	v_exp_f32_e32 v143, v143
	v_exp_f32_e32 v144, v144
	v_exp_f32_e32 v145, v145
	v_exp_f32_e32 v146, v146
	v_exp_f32_e32 v147, v147
	v_cvt_pk_bf16_f32 v190, v132, v133
	v_cvt_pk_bf16_f32 v191, v134, v135
	v_cvt_pk_bf16_f32 v192, v136, v137
	v_cvt_pk_bf16_f32 v193, v138, v139
	v_cvt_pk_bf16_f32 v206, v148, v149
	v_cvt_pk_bf16_f32 v207, v150, v151
	v_cvt_pk_bf16_f32 v208, v152, v153
	v_cvt_pk_bf16_f32 v209, v154, v155
	ds_read2_b64 v[232:235], v187 offset0:8 offset1:12
	s_waitcnt lgkmcnt(3)
	v_add_u32_e32 v187, 0x1100, v186
	v_mfma_f32_16x16x32_bf16 v[128:131], v[238:241], v[190:193], v[128:131]
	v_cvt_pk_bf16_f32 v210, v140, v141
	v_cvt_pk_bf16_f32 v211, v142, v143
	v_cvt_pk_bf16_f32 v212, v144, v145
	v_mfma_f32_16x16x32_bf16 v[32:35], v[238:241], v[206:209], v[32:35]
	ds_read2_b64 v[238:241], v187 offset1:4
	v_cvt_pk_bf16_f32 v213, v146, v147
	v_cvt_pk_bf16_f32 v202, v156, v157
	s_waitcnt lgkmcnt(3)
	v_cvt_pk_bf16_f32 v203, v158, v159
	v_cvt_pk_bf16_f32 v204, v160, v161
	v_cvt_pk_bf16_f32 v205, v162, v163
	v_mfma_f32_16x16x32_bf16 v[128:131], v[242:245], v[210:213], v[128:131]
	s_andn2_b64 vcc, exec, s[48:49]
	v_mfma_f32_16x16x32_bf16 v[32:35], v[242:245], v[202:205], v[32:35]
	ds_read2_b64 v[242:245], v187 offset0:8 offset1:12
	s_waitcnt lgkmcnt(3)
	v_add_u32_e32 v187, 0x1980, v186
	v_mfma_f32_16x16x32_bf16 v[124:127], v[246:249], v[190:193], v[124:127]
	v_mfma_f32_16x16x32_bf16 v[28:31], v[246:249], v[206:209], v[28:31]
	ds_read2_b64 v[246:249], v187 offset1:4
	s_waitcnt lgkmcnt(3)
	s_nop 0
	v_mfma_f32_16x16x32_bf16 v[124:127], v[232:235], v[210:213], v[124:127]
	v_mfma_f32_16x16x32_bf16 v[28:31], v[232:235], v[202:205], v[28:31]
	ds_read2_b64 v[232:235], v187 offset0:8 offset1:12
	s_waitcnt lgkmcnt(3)
	v_add_u32_e32 v187, 0x2200, v186
	v_mfma_f32_16x16x32_bf16 v[120:123], v[238:241], v[190:193], v[120:123]
	v_mfma_f32_16x16x32_bf16 v[24:27], v[238:241], v[206:209], v[24:27]
	ds_read2_b64 v[238:241], v187 offset1:4
	s_waitcnt lgkmcnt(3)
	s_nop 0
	v_mfma_f32_16x16x32_bf16 v[120:123], v[242:245], v[210:213], v[120:123]
	v_mfma_f32_16x16x32_bf16 v[24:27], v[242:245], v[202:205], v[24:27]
	ds_read2_b64 v[242:245], v187 offset0:8 offset1:12
	s_waitcnt lgkmcnt(3)
	v_add_u32_e32 v187, 0x2a80, v186
	v_mfma_f32_16x16x32_bf16 v[116:119], v[246:249], v[190:193], v[116:119]
	v_mfma_f32_16x16x32_bf16 v[20:23], v[246:249], v[206:209], v[20:23]
	ds_read2_b64 v[246:249], v187 offset1:4
	s_waitcnt lgkmcnt(3)
	s_nop 0
	v_mfma_f32_16x16x32_bf16 v[116:119], v[232:235], v[210:213], v[116:119]
	v_mfma_f32_16x16x32_bf16 v[20:23], v[232:235], v[202:205], v[20:23]
	ds_read2_b64 v[232:235], v187 offset0:8 offset1:12
	s_waitcnt lgkmcnt(3)
	v_add_u32_e32 v187, 0x3300, v186
	v_mfma_f32_16x16x32_bf16 v[80:83], v[238:241], v[190:193], v[80:83]
	v_add_u32_e32 v186, 0x3b80, v186
	v_mfma_f32_16x16x32_bf16 v[8:11], v[238:241], v[206:209], v[8:11]
	ds_read2_b64 v[238:241], v187 offset1:4
	s_waitcnt lgkmcnt(3)
	s_nop 0
	v_mfma_f32_16x16x32_bf16 v[80:83], v[242:245], v[210:213], v[80:83]
	v_mfma_f32_16x16x32_bf16 v[8:11], v[242:245], v[202:205], v[8:11]
	ds_read2_b64 v[242:245], v187 offset0:8 offset1:12
	s_waitcnt lgkmcnt(3)
	s_nop 0
	v_mfma_f32_16x16x32_bf16 v[56:59], v[246:249], v[190:193], v[56:59]
	v_mfma_f32_16x16x32_bf16 v[0:3], v[246:249], v[206:209], v[0:3]
	ds_read2_b64 v[246:249], v186 offset1:4
	s_waitcnt lgkmcnt(3)
	s_nop 0
	v_mfma_f32_16x16x32_bf16 v[56:59], v[232:235], v[210:213], v[56:59]
	v_mfma_f32_16x16x32_bf16 v[0:3], v[232:235], v[202:205], v[0:3]
	ds_read2_b64 v[232:235], v186 offset0:8 offset1:12
	s_waitcnt lgkmcnt(3)
	s_waitcnt lgkmcnt(2)
	s_waitcnt lgkmcnt(1)
	s_nop 0
	v_mfma_f32_16x16x32_bf16 v[40:43], v[238:241], v[190:193], v[40:43]
	s_waitcnt lgkmcnt(0)
	v_mfma_f32_16x16x32_bf16 v[12:15], v[238:241], v[206:209], v[12:15]
	v_mfma_f32_16x16x32_bf16 v[36:39], v[246:249], v[190:193], v[36:39]
	v_mfma_f32_16x16x32_bf16 v[4:7], v[246:249], v[206:209], v[4:7]
	v_mfma_f32_16x16x32_bf16 v[40:43], v[242:245], v[210:213], v[40:43]
	v_mfma_f32_16x16x32_bf16 v[12:15], v[242:245], v[202:205], v[12:15]
	v_mfma_f32_16x16x32_bf16 v[36:39], v[232:235], v[210:213], v[36:39]
	v_mfma_f32_16x16x32_bf16 v[4:7], v[232:235], v[202:205], v[4:7]
	s_cbranch_vccnz .LBB0_801
	s_bitcmp1_b32 s52, 0
	s_cselect_b32 s34, 0x8c00, 0
	v_add_u32_e32 v186, s34, v194
	v_add3_u32 v187, v186, v167, v168
	v_add3_u32 v186, v186, v171, v170
	ds_write_b128 v187, v[44:47]
	ds_write_b64 v186, v[52:53] offset:17408
	ds_write_b64 v186, v[54:55] offset:17416
	ds_write_b128 v187, v[48:51] offset:16
	ds_write_b64 v186, v[60:61] offset:17424
	ds_write_b64 v186, v[62:63] offset:17432
	ds_write_b128 v187, v[64:67] offset:32
	ds_write_b64 v186, v[72:73] offset:17440
	ds_write_b64 v186, v[74:75] offset:17448
	ds_write_b128 v187, v[68:71] offset:48
	ds_write_b64 v186, v[88:89] offset:17456
	ds_write_b64 v186, v[90:91] offset:17464

.LBB0_880:
	s_or_b64 exec, exec, s[40:41]
	s_waitcnt lgkmcnt(0)
	s_barrier
	ds_read_b32 v0, v230
	s_movk_i32 s25, 0x47f
	s_waitcnt lgkmcnt(0)
	v_cmp_lt_i32_e64 s[40:41], s25, v0
	v_readfirstlane_b32 s25, v0
	v_lshl_add_u32 v1, v0, 1, v216
	s_cmpk_lt_i32 s25, 0x480
	s_movk_i32 s25, 0x900
	s_cselect_b64 s[48:49], -1, 0
	v_cmp_gt_i32_e32 vcc, s25, v1
	s_and_b64 s[50:51], s[48:49], vcc
	s_and_saveexec_b64 s[48:49], s[50:51]
	s_cbranch_execz .LBB0_875
	s_waitcnt vmcnt(1)
	v_mov_b32_e32 v2, v217
	v_lshlrev_b32_e32 v0, 5, v0
	v_ashrrev_i32_e32 v3, 4, v2
	v_and_b32_e32 v7, -4, v3
	v_lshl_add_u32 v43, v1, 4, v7
	v_bfe_u32 v1, v2, 3, 3
	v_readlane_b32 s25, v255, 4
	v_add3_u32 v0, v228, v0, v7
	v_and_b32_e32 v6, 63, v2
	v_or_b32_e32 v2, s25, v1
	v_mad_i64_i32 v[0:1], s[50:51], v0, s33, 0
	v_mov_b32_e32 v3, v17
	v_readlane_b32 s50, v252, 19
	v_lshlrev_b32_e32 v16, 3, v6
	v_lshlrev_b32_e32 v4, 4, v6
	v_mov_b32_e32 v5, v17
	v_lshl_add_u64 v[28:29], v[2:3], 2, s[12:13]
	v_lshlrev_b32_e32 v2, 5, v6
	v_lshl_or_b32 v0, v6, 2, v0
	v_readlane_b32 s51, v252, 20
	v_lshl_add_u64 v[26:27], s[6:7], 0, v[4:5]
	v_lshl_add_u64 v[30:31], s[44:45], 0, v[2:3]
	v_lshl_add_u64 v[32:33], s[46:47], 0, v[16:17]
	v_lshl_add_u64 v[34:35], s[50:51], 0, v[0:1]
	s_mov_b32 s25, 0
	v_lshlrev_b32_e32 v16, 1, v16
	s_and_b64 vcc, exec, s[10:11]
	s_cbranch_vccnz .LBB0_883
	global_load_dwordx2 v[102:103], v[32:33], off
	s_mov_b64 s[52:53], 0xa921000
	v_lshl_add_u64 v[104:105], v[34:35], 0, s[52:53]
	s_mov_b64 s[52:53], 0x1800
	v_lshl_add_u64 v[106:107], v[104:105], 0, s[52:53]
	v_lshl_add_u64 v[108:109], v[106:107], 0, s[52:53]
	v_lshl_add_u64 v[110:111], v[108:109], 0, s[52:53]
	global_load_dword v54, v[104:105], off offset:0
	global_load_dword v55, v[104:105], off offset:1024
	global_load_dword v56, v[104:105], off offset:3072
	global_load_dword v57, v[104:105], off offset:256
	global_load_dword v58, v[104:105], off offset:1280
	global_load_dword v59, v[104:105], off offset:3328
	global_load_dword v60, v[104:105], off offset:512
	global_load_dword v61, v[104:105], off offset:1536
	global_load_dword v62, v[104:105], off offset:3584
	global_load_dword v63, v[104:105], off offset:768
	global_load_dword v64, v[104:105], off offset:1792
	global_load_dword v65, v[104:105], off offset:3840
	global_load_dword v66, v[106:107], off offset:0
	global_load_dword v67, v[106:107], off offset:1024
	global_load_dword v68, v[106:107], off offset:3072
	global_load_dword v69, v[106:107], off offset:256
	global_load_dword v70, v[106:107], off offset:1280
	global_load_dword v71, v[106:107], off offset:3328
	global_load_dword v72, v[106:107], off offset:512
	global_load_dword v73, v[106:107], off offset:1536
	global_load_dword v74, v[106:107], off offset:3584
	global_load_dword v75, v[106:107], off offset:768
	global_load_dword v76, v[106:107], off offset:1792
	global_load_dword v77, v[106:107], off offset:3840
	global_load_dword v78, v[108:109], off offset:0
	global_load_dword v79, v[108:109], off offset:1024
	global_load_dword v80, v[108:109], off offset:3072
	global_load_dword v81, v[108:109], off offset:256
	global_load_dword v82, v[108:109], off offset:1280
	global_load_dword v83, v[108:109], off offset:3328
	global_load_dword v84, v[108:109], off offset:512
	global_load_dword v85, v[108:109], off offset:1536
	global_load_dword v86, v[108:109], off offset:3584
	global_load_dword v87, v[108:109], off offset:768
	global_load_dword v88, v[108:109], off offset:1792
	global_load_dword v89, v[108:109], off offset:3840
	global_load_dword v90, v[110:111], off offset:0
	global_load_dword v91, v[110:111], off offset:1024
	global_load_dword v92, v[110:111], off offset:3072
	global_load_dword v93, v[110:111], off offset:256
	global_load_dword v94, v[110:111], off offset:1280
	global_load_dword v95, v[110:111], off offset:3328
	global_load_dword v96, v[110:111], off offset:512
	global_load_dword v97, v[110:111], off offset:1536
	global_load_dword v98, v[110:111], off offset:3584
	global_load_dword v99, v[110:111], off offset:768
	global_load_dword v100, v[110:111], off offset:1792
	global_load_dword v101, v[110:111], off offset:3840
	s_waitcnt vmcnt(45)
	v_lshlrev_b32_e32 v112, 16, v54
	v_lshlrev_b32_e32 v114, 16, v55
	v_lshlrev_b32_e32 v120, 16, v56
	v_and_b32_e32 v121, 0xffff0000, v56
	v_and_b32_e32 v113, 0xffff0000, v54
	v_and_b32_e32 v115, 0xffff0000, v55
	v_pk_add_f32 v[112:113], v[112:113], v[114:115]
	s_nop 0
	v_pk_mul_f32 v[114:115], v[112:113], v[112:113]
	s_nop 0
	v_add_f32_e32 v114, v114, v115
	s_nop 1
	v_add_f32_dpp v114, v114, v114 quad_perm:[1,0,3,2] row_mask:0xf bank_mask:0xf
	s_nop 1
	v_add_f32_dpp v114, v114, v114 quad_perm:[2,3,0,1] row_mask:0xf bank_mask:0xf
	s_nop 1
	v_add_f32_dpp v114, v114, v114 row_half_mirror row_mask:0xf bank_mask:0xf
	s_nop 1
	v_add_f32_dpp v114, v114, v114 row_mirror row_mask:0xf bank_mask:0xf
	v_mov_b32_e32 v115, v114
	s_nop 1
	v_permlane16_swap_b32_e32 v114, v115
	v_add_f32_e32 v114, v114, v115
	v_mov_b32_e32 v115, v114
	s_nop 1
	v_permlane32_swap_b32_e32 v114, v115
	v_add_f32_e32 v114, v114, v115
	v_fmamk_f32 v114, v114, 0x3c000000, v231
	v_cmp_gt_f32_e32 vcc, s3, v114
	v_mul_f32_e32 v115, 0x4b800000, v114
	s_nop 0
	v_cndmask_b32_e32 v114, v114, v115, vcc
	v_rsq_f32_e32 v114, v114
	s_nop 0
	v_mul_f32_e32 v115, 0x45800000, v114
	v_cndmask_b32_e32 v114, v114, v115, vcc
	v_mul_f32_e32 v115, 0xbfb8aa3b, v120
	v_pk_mul_f32 v[112:113], v[112:113], v[114:115] op_sel_hi:[1,0]
	v_mul_f32_e32 v114, 0xbfb8aa3b, v121
	v_exp_f32_e32 v118, v115
	v_exp_f32_e32 v119, v114
	v_pk_mul_f32 v[112:113], v[102:103], v[112:113]
	v_pk_add_f32 v[114:115], v[118:119], 1.0 op_sel_hi:[1,0]
	s_nop 0
	v_div_scale_f32 v116, s[52:53], v115, v115, v121
	v_rcp_f32_e32 v117, v116
	s_nop 0
	v_fma_f32 v118, -v116, v117, 1.0
	v_fmac_f32_e32 v117, v118, v117
	v_div_scale_f32 v118, vcc, v121, v115, v121
	v_mul_f32_e32 v119, v118, v117
	v_fma_f32 v122, -v116, v119, v118
	v_fmac_f32_e32 v119, v122, v117
	v_fma_f32 v116, -v116, v119, v118
	v_div_fmas_f32 v116, v116, v117, v119
	v_div_fixup_f32 v115, v116, v115, v121
	v_div_scale_f32 v116, s[52:53], v114, v114, v120
	v_rcp_f32_e32 v117, v116
	s_nop 0
	v_fma_f32 v118, -v116, v117, 1.0
	v_fmac_f32_e32 v117, v118, v117
	v_div_scale_f32 v118, vcc, v120, v114, v120
	v_mul_f32_e32 v119, v118, v117
	v_fma_f32 v122, -v116, v119, v118
	v_fmac_f32_e32 v119, v122, v117
	v_fma_f32 v116, -v116, v119, v118
	v_div_fmas_f32 v116, v116, v117, v119
	v_div_fixup_f32 v114, v116, v114, v120
	v_pk_mul_f32 v[112:113], v[114:115], v[112:113]
	s_nop 0
	v_cvt_pk_bf16_f32 v112, v112, v113
	global_store_dword v[104:105], v112, off offset:0
	s_waitcnt vmcnt(43)
	v_lshlrev_b32_e32 v112, 16, v57
	v_lshlrev_b32_e32 v114, 16, v58
	v_lshlrev_b32_e32 v120, 16, v59
	v_and_b32_e32 v121, 0xffff0000, v59
	v_and_b32_e32 v113, 0xffff0000, v57
	v_and_b32_e32 v115, 0xffff0000, v58
	v_pk_add_f32 v[112:113], v[112:113], v[114:115]
	s_nop 0
	v_pk_mul_f32 v[114:115], v[112:113], v[112:113]
	s_nop 0
	v_add_f32_e32 v114, v114, v115
	s_nop 1
	v_add_f32_dpp v114, v114, v114 quad_perm:[1,0,3,2] row_mask:0xf bank_mask:0xf
	s_nop 1
	v_add_f32_dpp v114, v114, v114 quad_perm:[2,3,0,1] row_mask:0xf bank_mask:0xf
	s_nop 1
	v_add_f32_dpp v114, v114, v114 row_half_mirror row_mask:0xf bank_mask:0xf
	s_nop 1
	v_add_f32_dpp v114, v114, v114 row_mirror row_mask:0xf bank_mask:0xf
	v_mov_b32_e32 v115, v114
	s_nop 1
	v_permlane16_swap_b32_e32 v114, v115
	v_add_f32_e32 v114, v114, v115
	v_mov_b32_e32 v115, v114
	s_nop 1
	v_permlane32_swap_b32_e32 v114, v115
	v_add_f32_e32 v114, v114, v115
	v_fmamk_f32 v114, v114, 0x3c000000, v231
	v_cmp_gt_f32_e32 vcc, s3, v114
	v_mul_f32_e32 v115, 0x4b800000, v114
	s_nop 0
	v_cndmask_b32_e32 v114, v114, v115, vcc
	v_rsq_f32_e32 v114, v114
	s_nop 0
	v_mul_f32_e32 v115, 0x45800000, v114
	v_cndmask_b32_e32 v114, v114, v115, vcc
	v_mul_f32_e32 v115, 0xbfb8aa3b, v120
	v_pk_mul_f32 v[112:113], v[112:113], v[114:115] op_sel_hi:[1,0]
	v_mul_f32_e32 v114, 0xbfb8aa3b, v121
	v_exp_f32_e32 v118, v115
	v_exp_f32_e32 v119, v114
	v_pk_mul_f32 v[112:113], v[102:103], v[112:113]
	v_pk_add_f32 v[114:115], v[118:119], 1.0 op_sel_hi:[1,0]
	s_nop 0
	v_div_scale_f32 v116, s[52:53], v115, v115, v121
	v_rcp_f32_e32 v117, v116
	s_nop 0
	v_fma_f32 v118, -v116, v117, 1.0
	v_fmac_f32_e32 v117, v118, v117
	v_div_scale_f32 v118, vcc, v121, v115, v121
	v_mul_f32_e32 v119, v118, v117
	v_fma_f32 v122, -v116, v119, v118
	v_fmac_f32_e32 v119, v122, v117
	v_fma_f32 v116, -v116, v119, v118
	v_div_fmas_f32 v116, v116, v117, v119
	v_div_fixup_f32 v115, v116, v115, v121
	v_div_scale_f32 v116, s[52:53], v114, v114, v120
	v_rcp_f32_e32 v117, v116
	s_nop 0
	v_fma_f32 v118, -v116, v117, 1.0
	v_fmac_f32_e32 v117, v118, v117
	v_div_scale_f32 v118, vcc, v120, v114, v120
	v_mul_f32_e32 v119, v118, v117
	v_fma_f32 v122, -v116, v119, v118
	v_fmac_f32_e32 v119, v122, v117
	v_fma_f32 v116, -v116, v119, v118
	v_div_fmas_f32 v116, v116, v117, v119
	v_div_fixup_f32 v114, v116, v114, v120
	v_pk_mul_f32 v[112:113], v[114:115], v[112:113]
	s_nop 0
	v_cvt_pk_bf16_f32 v112, v112, v113
	global_store_dword v[104:105], v112, off offset:256
	s_waitcnt vmcnt(41)
	v_lshlrev_b32_e32 v112, 16, v60
	v_lshlrev_b32_e32 v114, 16, v61
	v_lshlrev_b32_e32 v120, 16, v62
	v_and_b32_e32 v121, 0xffff0000, v62
	v_and_b32_e32 v113, 0xffff0000, v60
	v_and_b32_e32 v115, 0xffff0000, v61
	v_pk_add_f32 v[112:113], v[112:113], v[114:115]
	s_nop 0
	v_pk_mul_f32 v[114:115], v[112:113], v[112:113]
	s_nop 0
	v_add_f32_e32 v114, v114, v115
	s_nop 1
	v_add_f32_dpp v114, v114, v114 quad_perm:[1,0,3,2] row_mask:0xf bank_mask:0xf
	s_nop 1
	v_add_f32_dpp v114, v114, v114 quad_perm:[2,3,0,1] row_mask:0xf bank_mask:0xf
	s_nop 1
	v_add_f32_dpp v114, v114, v114 row_half_mirror row_mask:0xf bank_mask:0xf
	s_nop 1
	v_add_f32_dpp v114, v114, v114 row_mirror row_mask:0xf bank_mask:0xf
	v_mov_b32_e32 v115, v114
	s_nop 1
	v_permlane16_swap_b32_e32 v114, v115
	v_add_f32_e32 v114, v114, v115
	v_mov_b32_e32 v115, v114
	s_nop 1
	v_permlane32_swap_b32_e32 v114, v115
	v_add_f32_e32 v114, v114, v115
	v_fmamk_f32 v114, v114, 0x3c000000, v231
	v_cmp_gt_f32_e32 vcc, s3, v114
	v_mul_f32_e32 v115, 0x4b800000, v114
	s_nop 0
	v_cndmask_b32_e32 v114, v114, v115, vcc
	v_rsq_f32_e32 v114, v114
	s_nop 0
	v_mul_f32_e32 v115, 0x45800000, v114
	v_cndmask_b32_e32 v114, v114, v115, vcc
	v_mul_f32_e32 v115, 0xbfb8aa3b, v120
	v_pk_mul_f32 v[112:113], v[112:113], v[114:115] op_sel_hi:[1,0]
	v_mul_f32_e32 v114, 0xbfb8aa3b, v121
	v_exp_f32_e32 v118, v115
	v_exp_f32_e32 v119, v114
	v_pk_mul_f32 v[112:113], v[102:103], v[112:113]
	v_pk_add_f32 v[114:115], v[118:119], 1.0 op_sel_hi:[1,0]
	s_nop 0
	v_div_scale_f32 v116, s[52:53], v115, v115, v121
	v_rcp_f32_e32 v117, v116
	s_nop 0
	v_fma_f32 v118, -v116, v117, 1.0
	v_fmac_f32_e32 v117, v118, v117
	v_div_scale_f32 v118, vcc, v121, v115, v121
	v_mul_f32_e32 v119, v118, v117
	v_fma_f32 v122, -v116, v119, v118
	v_fmac_f32_e32 v119, v122, v117
	v_fma_f32 v116, -v116, v119, v118
	v_div_fmas_f32 v116, v116, v117, v119
	v_div_fixup_f32 v115, v116, v115, v121
	v_div_scale_f32 v116, s[52:53], v114, v114, v120
	v_rcp_f32_e32 v117, v116
	s_nop 0
	v_fma_f32 v118, -v116, v117, 1.0
	v_fmac_f32_e32 v117, v118, v117
	v_div_scale_f32 v118, vcc, v120, v114, v120
	v_mul_f32_e32 v119, v118, v117
	v_fma_f32 v122, -v116, v119, v118
	v_fmac_f32_e32 v119, v122, v117
	v_fma_f32 v116, -v116, v119, v118
	v_div_fmas_f32 v116, v116, v117, v119
	v_div_fixup_f32 v114, v116, v114, v120
	v_pk_mul_f32 v[112:113], v[114:115], v[112:113]
	s_nop 0
	v_cvt_pk_bf16_f32 v112, v112, v113
	global_store_dword v[104:105], v112, off offset:512
	s_waitcnt vmcnt(39)
	v_lshlrev_b32_e32 v112, 16, v63
	v_lshlrev_b32_e32 v114, 16, v64
	v_lshlrev_b32_e32 v120, 16, v65
	v_and_b32_e32 v121, 0xffff0000, v65
	v_and_b32_e32 v113, 0xffff0000, v63
	v_and_b32_e32 v115, 0xffff0000, v64
	v_pk_add_f32 v[112:113], v[112:113], v[114:115]
	s_nop 0
	v_pk_mul_f32 v[114:115], v[112:113], v[112:113]
	s_nop 0
	v_add_f32_e32 v114, v114, v115
	s_nop 1
	v_add_f32_dpp v114, v114, v114 quad_perm:[1,0,3,2] row_mask:0xf bank_mask:0xf
	s_nop 1
	v_add_f32_dpp v114, v114, v114 quad_perm:[2,3,0,1] row_mask:0xf bank_mask:0xf
	s_nop 1
	v_add_f32_dpp v114, v114, v114 row_half_mirror row_mask:0xf bank_mask:0xf
	s_nop 1
	v_add_f32_dpp v114, v114, v114 row_mirror row_mask:0xf bank_mask:0xf
	v_mov_b32_e32 v115, v114
	s_nop 1
	v_permlane16_swap_b32_e32 v114, v115
	v_add_f32_e32 v114, v114, v115
	v_mov_b32_e32 v115, v114
	s_nop 1
	v_permlane32_swap_b32_e32 v114, v115
	v_add_f32_e32 v114, v114, v115
	v_fmamk_f32 v114, v114, 0x3c000000, v231
	v_cmp_gt_f32_e32 vcc, s3, v114
	v_mul_f32_e32 v115, 0x4b800000, v114
	s_nop 0
	v_cndmask_b32_e32 v114, v114, v115, vcc
	v_rsq_f32_e32 v114, v114
	s_nop 0
	v_mul_f32_e32 v115, 0x45800000, v114
	v_cndmask_b32_e32 v114, v114, v115, vcc
	v_mul_f32_e32 v115, 0xbfb8aa3b, v120
	v_pk_mul_f32 v[112:113], v[112:113], v[114:115] op_sel_hi:[1,0]
	v_mul_f32_e32 v114, 0xbfb8aa3b, v121
	v_exp_f32_e32 v118, v115
	v_exp_f32_e32 v119, v114
	v_pk_mul_f32 v[112:113], v[102:103], v[112:113]
	v_pk_add_f32 v[114:115], v[118:119], 1.0 op_sel_hi:[1,0]
	s_nop 0
	v_div_scale_f32 v116, s[52:53], v115, v115, v121
	v_rcp_f32_e32 v117, v116
	s_nop 0
	v_fma_f32 v118, -v116, v117, 1.0
	v_fmac_f32_e32 v117, v118, v117
	v_div_scale_f32 v118, vcc, v121, v115, v121
	v_mul_f32_e32 v119, v118, v117
	v_fma_f32 v122, -v116, v119, v118
	v_fmac_f32_e32 v119, v122, v117
	v_fma_f32 v116, -v116, v119, v118
	v_div_fmas_f32 v116, v116, v117, v119
	v_div_fixup_f32 v115, v116, v115, v121
	v_div_scale_f32 v116, s[52:53], v114, v114, v120
	v_rcp_f32_e32 v117, v116
	s_nop 0
	v_fma_f32 v118, -v116, v117, 1.0
	v_fmac_f32_e32 v117, v118, v117
	v_div_scale_f32 v118, vcc, v120, v114, v120
	v_mul_f32_e32 v119, v118, v117
	v_fma_f32 v122, -v116, v119, v118
	v_fmac_f32_e32 v119, v122, v117
	v_fma_f32 v116, -v116, v119, v118
	v_div_fmas_f32 v116, v116, v117, v119
	v_div_fixup_f32 v114, v116, v114, v120
	v_pk_mul_f32 v[112:113], v[114:115], v[112:113]
	s_nop 0
	v_cvt_pk_bf16_f32 v112, v112, v113
	global_store_dword v[104:105], v112, off offset:768
	s_waitcnt vmcnt(37)
	v_lshlrev_b32_e32 v112, 16, v66
	v_lshlrev_b32_e32 v114, 16, v67
	v_lshlrev_b32_e32 v120, 16, v68
	v_and_b32_e32 v121, 0xffff0000, v68
	v_and_b32_e32 v113, 0xffff0000, v66
	v_and_b32_e32 v115, 0xffff0000, v67
	v_pk_add_f32 v[112:113], v[112:113], v[114:115]
	s_nop 0
	v_pk_mul_f32 v[114:115], v[112:113], v[112:113]
	s_nop 0
	v_add_f32_e32 v114, v114, v115
	s_nop 1
	v_add_f32_dpp v114, v114, v114 quad_perm:[1,0,3,2] row_mask:0xf bank_mask:0xf
	s_nop 1
	v_add_f32_dpp v114, v114, v114 quad_perm:[2,3,0,1] row_mask:0xf bank_mask:0xf
	s_nop 1
	v_add_f32_dpp v114, v114, v114 row_half_mirror row_mask:0xf bank_mask:0xf
	s_nop 1
	v_add_f32_dpp v114, v114, v114 row_mirror row_mask:0xf bank_mask:0xf
	v_mov_b32_e32 v115, v114
	s_nop 1
	v_permlane16_swap_b32_e32 v114, v115
	v_add_f32_e32 v114, v114, v115
	v_mov_b32_e32 v115, v114
	s_nop 1
	v_permlane32_swap_b32_e32 v114, v115
	v_add_f32_e32 v114, v114, v115
	v_fmamk_f32 v114, v114, 0x3c000000, v231
	v_cmp_gt_f32_e32 vcc, s3, v114
	v_mul_f32_e32 v115, 0x4b800000, v114
	s_nop 0
	v_cndmask_b32_e32 v114, v114, v115, vcc
	v_rsq_f32_e32 v114, v114
	s_nop 0
	v_mul_f32_e32 v115, 0x45800000, v114
	v_cndmask_b32_e32 v114, v114, v115, vcc
	v_mul_f32_e32 v115, 0xbfb8aa3b, v120
	v_pk_mul_f32 v[112:113], v[112:113], v[114:115] op_sel_hi:[1,0]
	v_mul_f32_e32 v114, 0xbfb8aa3b, v121
	v_exp_f32_e32 v118, v115
	v_exp_f32_e32 v119, v114
	v_pk_mul_f32 v[112:113], v[102:103], v[112:113]
	v_pk_add_f32 v[114:115], v[118:119], 1.0 op_sel_hi:[1,0]
	s_nop 0
	v_div_scale_f32 v116, s[52:53], v115, v115, v121
	v_rcp_f32_e32 v117, v116
	s_nop 0
	v_fma_f32 v118, -v116, v117, 1.0
	v_fmac_f32_e32 v117, v118, v117
	v_div_scale_f32 v118, vcc, v121, v115, v121
	v_mul_f32_e32 v119, v118, v117
	v_fma_f32 v122, -v116, v119, v118
	v_fmac_f32_e32 v119, v122, v117
	v_fma_f32 v116, -v116, v119, v118
	v_div_fmas_f32 v116, v116, v117, v119
	v_div_fixup_f32 v115, v116, v115, v121
	v_div_scale_f32 v116, s[52:53], v114, v114, v120
	v_rcp_f32_e32 v117, v116
	s_nop 0
	v_fma_f32 v118, -v116, v117, 1.0
	v_fmac_f32_e32 v117, v118, v117
	v_div_scale_f32 v118, vcc, v120, v114, v120
	v_mul_f32_e32 v119, v118, v117
	v_fma_f32 v122, -v116, v119, v118
	v_fmac_f32_e32 v119, v122, v117
	v_fma_f32 v116, -v116, v119, v118
	v_div_fmas_f32 v116, v116, v117, v119
	v_div_fixup_f32 v114, v116, v114, v120
	v_pk_mul_f32 v[112:113], v[114:115], v[112:113]
	s_nop 0
	v_cvt_pk_bf16_f32 v112, v112, v113
	global_store_dword v[106:107], v112, off offset:0
	s_waitcnt vmcnt(35)
	v_lshlrev_b32_e32 v112, 16, v69
	v_lshlrev_b32_e32 v114, 16, v70
	v_lshlrev_b32_e32 v120, 16, v71
	v_and_b32_e32 v121, 0xffff0000, v71
	v_and_b32_e32 v113, 0xffff0000, v69
	v_and_b32_e32 v115, 0xffff0000, v70
	v_pk_add_f32 v[112:113], v[112:113], v[114:115]
	s_nop 0
	v_pk_mul_f32 v[114:115], v[112:113], v[112:113]
	s_nop 0
	v_add_f32_e32 v114, v114, v115
	s_nop 1
	v_add_f32_dpp v114, v114, v114 quad_perm:[1,0,3,2] row_mask:0xf bank_mask:0xf
	s_nop 1
	v_add_f32_dpp v114, v114, v114 quad_perm:[2,3,0,1] row_mask:0xf bank_mask:0xf
	s_nop 1
	v_add_f32_dpp v114, v114, v114 row_half_mirror row_mask:0xf bank_mask:0xf
	s_nop 1
	v_add_f32_dpp v114, v114, v114 row_mirror row_mask:0xf bank_mask:0xf
	v_mov_b32_e32 v115, v114
	s_nop 1
	v_permlane16_swap_b32_e32 v114, v115
	v_add_f32_e32 v114, v114, v115
	v_mov_b32_e32 v115, v114
	s_nop 1
	v_permlane32_swap_b32_e32 v114, v115
	v_add_f32_e32 v114, v114, v115
	v_fmamk_f32 v114, v114, 0x3c000000, v231
	v_cmp_gt_f32_e32 vcc, s3, v114
	v_mul_f32_e32 v115, 0x4b800000, v114
	s_nop 0
	v_cndmask_b32_e32 v114, v114, v115, vcc
	v_rsq_f32_e32 v114, v114
	s_nop 0
	v_mul_f32_e32 v115, 0x45800000, v114
	v_cndmask_b32_e32 v114, v114, v115, vcc
	v_mul_f32_e32 v115, 0xbfb8aa3b, v120
	v_pk_mul_f32 v[112:113], v[112:113], v[114:115] op_sel_hi:[1,0]
	v_mul_f32_e32 v114, 0xbfb8aa3b, v121
	v_exp_f32_e32 v118, v115
	v_exp_f32_e32 v119, v114
	v_pk_mul_f32 v[112:113], v[102:103], v[112:113]
	v_pk_add_f32 v[114:115], v[118:119], 1.0 op_sel_hi:[1,0]
	s_nop 0
	v_div_scale_f32 v116, s[52:53], v115, v115, v121
	v_rcp_f32_e32 v117, v116
	s_nop 0
	v_fma_f32 v118, -v116, v117, 1.0
	v_fmac_f32_e32 v117, v118, v117
	v_div_scale_f32 v118, vcc, v121, v115, v121
	v_mul_f32_e32 v119, v118, v117
	v_fma_f32 v122, -v116, v119, v118
	v_fmac_f32_e32 v119, v122, v117
	v_fma_f32 v116, -v116, v119, v118
	v_div_fmas_f32 v116, v116, v117, v119
	v_div_fixup_f32 v115, v116, v115, v121
	v_div_scale_f32 v116, s[52:53], v114, v114, v120
	v_rcp_f32_e32 v117, v116
	s_nop 0
	v_fma_f32 v118, -v116, v117, 1.0
	v_fmac_f32_e32 v117, v118, v117
	v_div_scale_f32 v118, vcc, v120, v114, v120
	v_mul_f32_e32 v119, v118, v117
	v_fma_f32 v122, -v116, v119, v118
	v_fmac_f32_e32 v119, v122, v117
	v_fma_f32 v116, -v116, v119, v118
	v_div_fmas_f32 v116, v116, v117, v119
	v_div_fixup_f32 v114, v116, v114, v120
	v_pk_mul_f32 v[112:113], v[114:115], v[112:113]
	s_nop 0
	v_cvt_pk_bf16_f32 v112, v112, v113
	global_store_dword v[106:107], v112, off offset:256
	s_waitcnt vmcnt(33)
	v_lshlrev_b32_e32 v112, 16, v72
	v_lshlrev_b32_e32 v114, 16, v73
	v_lshlrev_b32_e32 v120, 16, v74
	v_and_b32_e32 v121, 0xffff0000, v74
	v_and_b32_e32 v113, 0xffff0000, v72
	v_and_b32_e32 v115, 0xffff0000, v73
	v_pk_add_f32 v[112:113], v[112:113], v[114:115]
	s_nop 0
	v_pk_mul_f32 v[114:115], v[112:113], v[112:113]
	s_nop 0
	v_add_f32_e32 v114, v114, v115
	s_nop 1
	v_add_f32_dpp v114, v114, v114 quad_perm:[1,0,3,2] row_mask:0xf bank_mask:0xf
	s_nop 1
	v_add_f32_dpp v114, v114, v114 quad_perm:[2,3,0,1] row_mask:0xf bank_mask:0xf
	s_nop 1
	v_add_f32_dpp v114, v114, v114 row_half_mirror row_mask:0xf bank_mask:0xf
	s_nop 1
	v_add_f32_dpp v114, v114, v114 row_mirror row_mask:0xf bank_mask:0xf
	v_mov_b32_e32 v115, v114
	s_nop 1
	v_permlane16_swap_b32_e32 v114, v115
	v_add_f32_e32 v114, v114, v115
	v_mov_b32_e32 v115, v114
	s_nop 1
	v_permlane32_swap_b32_e32 v114, v115
	v_add_f32_e32 v114, v114, v115
	v_fmamk_f32 v114, v114, 0x3c000000, v231
	v_cmp_gt_f32_e32 vcc, s3, v114
	v_mul_f32_e32 v115, 0x4b800000, v114
	s_nop 0
	v_cndmask_b32_e32 v114, v114, v115, vcc
	v_rsq_f32_e32 v114, v114
	s_nop 0
	v_mul_f32_e32 v115, 0x45800000, v114
	v_cndmask_b32_e32 v114, v114, v115, vcc
	v_mul_f32_e32 v115, 0xbfb8aa3b, v120
	v_pk_mul_f32 v[112:113], v[112:113], v[114:115] op_sel_hi:[1,0]
	v_mul_f32_e32 v114, 0xbfb8aa3b, v121
	v_exp_f32_e32 v118, v115
	v_exp_f32_e32 v119, v114
	v_pk_mul_f32 v[112:113], v[102:103], v[112:113]
	v_pk_add_f32 v[114:115], v[118:119], 1.0 op_sel_hi:[1,0]
	s_nop 0
	v_div_scale_f32 v116, s[52:53], v115, v115, v121
	v_rcp_f32_e32 v117, v116
	s_nop 0
	v_fma_f32 v118, -v116, v117, 1.0
	v_fmac_f32_e32 v117, v118, v117
	v_div_scale_f32 v118, vcc, v121, v115, v121
	v_mul_f32_e32 v119, v118, v117
	v_fma_f32 v122, -v116, v119, v118
	v_fmac_f32_e32 v119, v122, v117
	v_fma_f32 v116, -v116, v119, v118
	v_div_fmas_f32 v116, v116, v117, v119
	v_div_fixup_f32 v115, v116, v115, v121
	v_div_scale_f32 v116, s[52:53], v114, v114, v120
	v_rcp_f32_e32 v117, v116
	s_nop 0
	v_fma_f32 v118, -v116, v117, 1.0
	v_fmac_f32_e32 v117, v118, v117
	v_div_scale_f32 v118, vcc, v120, v114, v120
	v_mul_f32_e32 v119, v118, v117
	v_fma_f32 v122, -v116, v119, v118
	v_fmac_f32_e32 v119, v122, v117
	v_fma_f32 v116, -v116, v119, v118
	v_div_fmas_f32 v116, v116, v117, v119
	v_div_fixup_f32 v114, v116, v114, v120
	v_pk_mul_f32 v[112:113], v[114:115], v[112:113]
	s_nop 0
	v_cvt_pk_bf16_f32 v112, v112, v113
	global_store_dword v[106:107], v112, off offset:512
	s_waitcnt vmcnt(31)
	v_lshlrev_b32_e32 v112, 16, v75
	v_lshlrev_b32_e32 v114, 16, v76
	v_lshlrev_b32_e32 v120, 16, v77
	v_and_b32_e32 v121, 0xffff0000, v77
	v_and_b32_e32 v113, 0xffff0000, v75
	v_and_b32_e32 v115, 0xffff0000, v76
	v_pk_add_f32 v[112:113], v[112:113], v[114:115]
	s_nop 0
	v_pk_mul_f32 v[114:115], v[112:113], v[112:113]
	s_nop 0
	v_add_f32_e32 v114, v114, v115
	s_nop 1
	v_add_f32_dpp v114, v114, v114 quad_perm:[1,0,3,2] row_mask:0xf bank_mask:0xf
	s_nop 1
	v_add_f32_dpp v114, v114, v114 quad_perm:[2,3,0,1] row_mask:0xf bank_mask:0xf
	s_nop 1
	v_add_f32_dpp v114, v114, v114 row_half_mirror row_mask:0xf bank_mask:0xf
	s_nop 1
	v_add_f32_dpp v114, v114, v114 row_mirror row_mask:0xf bank_mask:0xf
	v_mov_b32_e32 v115, v114
	s_nop 1
	v_permlane16_swap_b32_e32 v114, v115
	v_add_f32_e32 v114, v114, v115
	v_mov_b32_e32 v115, v114
	s_nop 1
	v_permlane32_swap_b32_e32 v114, v115
	v_add_f32_e32 v114, v114, v115
	v_fmamk_f32 v114, v114, 0x3c000000, v231
	v_cmp_gt_f32_e32 vcc, s3, v114
	v_mul_f32_e32 v115, 0x4b800000, v114
	s_nop 0
	v_cndmask_b32_e32 v114, v114, v115, vcc
	v_rsq_f32_e32 v114, v114
	s_nop 0
	v_mul_f32_e32 v115, 0x45800000, v114
	v_cndmask_b32_e32 v114, v114, v115, vcc
	v_mul_f32_e32 v115, 0xbfb8aa3b, v120
	v_pk_mul_f32 v[112:113], v[112:113], v[114:115] op_sel_hi:[1,0]
	v_mul_f32_e32 v114, 0xbfb8aa3b, v121
	v_exp_f32_e32 v118, v115
	v_exp_f32_e32 v119, v114
	v_pk_mul_f32 v[112:113], v[102:103], v[112:113]
	v_pk_add_f32 v[114:115], v[118:119], 1.0 op_sel_hi:[1,0]
	s_nop 0
	v_div_scale_f32 v116, s[52:53], v115, v115, v121
	v_rcp_f32_e32 v117, v116
	s_nop 0
	v_fma_f32 v118, -v116, v117, 1.0
	v_fmac_f32_e32 v117, v118, v117
	v_div_scale_f32 v118, vcc, v121, v115, v121
	v_mul_f32_e32 v119, v118, v117
	v_fma_f32 v122, -v116, v119, v118
	v_fmac_f32_e32 v119, v122, v117
	v_fma_f32 v116, -v116, v119, v118
	v_div_fmas_f32 v116, v116, v117, v119
	v_div_fixup_f32 v115, v116, v115, v121
	v_div_scale_f32 v116, s[52:53], v114, v114, v120
	v_rcp_f32_e32 v117, v116
	s_nop 0
	v_fma_f32 v118, -v116, v117, 1.0
	v_fmac_f32_e32 v117, v118, v117
	v_div_scale_f32 v118, vcc, v120, v114, v120
	v_mul_f32_e32 v119, v118, v117
	v_fma_f32 v122, -v116, v119, v118
	v_fmac_f32_e32 v119, v122, v117
	v_fma_f32 v116, -v116, v119, v118
	v_div_fmas_f32 v116, v116, v117, v119
	v_div_fixup_f32 v114, v116, v114, v120
	v_pk_mul_f32 v[112:113], v[114:115], v[112:113]
	s_nop 0
	v_cvt_pk_bf16_f32 v112, v112, v113
	global_store_dword v[106:107], v112, off offset:768
	s_waitcnt vmcnt(29)
	v_lshlrev_b32_e32 v112, 16, v78
	v_lshlrev_b32_e32 v114, 16, v79
	v_lshlrev_b32_e32 v120, 16, v80
	v_and_b32_e32 v121, 0xffff0000, v80
	v_and_b32_e32 v113, 0xffff0000, v78
	v_and_b32_e32 v115, 0xffff0000, v79
	v_pk_add_f32 v[112:113], v[112:113], v[114:115]
	s_nop 0
	v_pk_mul_f32 v[114:115], v[112:113], v[112:113]
	s_nop 0
	v_add_f32_e32 v114, v114, v115
	s_nop 1
	v_add_f32_dpp v114, v114, v114 quad_perm:[1,0,3,2] row_mask:0xf bank_mask:0xf
	s_nop 1
	v_add_f32_dpp v114, v114, v114 quad_perm:[2,3,0,1] row_mask:0xf bank_mask:0xf
	s_nop 1
	v_add_f32_dpp v114, v114, v114 row_half_mirror row_mask:0xf bank_mask:0xf
	s_nop 1
	v_add_f32_dpp v114, v114, v114 row_mirror row_mask:0xf bank_mask:0xf
	v_mov_b32_e32 v115, v114
	s_nop 1
	v_permlane16_swap_b32_e32 v114, v115
	v_add_f32_e32 v114, v114, v115
	v_mov_b32_e32 v115, v114
	s_nop 1
	v_permlane32_swap_b32_e32 v114, v115
	v_add_f32_e32 v114, v114, v115
	v_fmamk_f32 v114, v114, 0x3c000000, v231
	v_cmp_gt_f32_e32 vcc, s3, v114
	v_mul_f32_e32 v115, 0x4b800000, v114
	s_nop 0
	v_cndmask_b32_e32 v114, v114, v115, vcc
	v_rsq_f32_e32 v114, v114
	s_nop 0
	v_mul_f32_e32 v115, 0x45800000, v114
	v_cndmask_b32_e32 v114, v114, v115, vcc
	v_mul_f32_e32 v115, 0xbfb8aa3b, v120
	v_pk_mul_f32 v[112:113], v[112:113], v[114:115] op_sel_hi:[1,0]
	v_mul_f32_e32 v114, 0xbfb8aa3b, v121
	v_exp_f32_e32 v118, v115
	v_exp_f32_e32 v119, v114
	v_pk_mul_f32 v[112:113], v[102:103], v[112:113]
	v_pk_add_f32 v[114:115], v[118:119], 1.0 op_sel_hi:[1,0]
	s_nop 0
	v_div_scale_f32 v116, s[52:53], v115, v115, v121
	v_rcp_f32_e32 v117, v116
	s_nop 0
	v_fma_f32 v118, -v116, v117, 1.0
	v_fmac_f32_e32 v117, v118, v117
	v_div_scale_f32 v118, vcc, v121, v115, v121
	v_mul_f32_e32 v119, v118, v117
	v_fma_f32 v122, -v116, v119, v118
	v_fmac_f32_e32 v119, v122, v117
	v_fma_f32 v116, -v116, v119, v118
	v_div_fmas_f32 v116, v116, v117, v119
	v_div_fixup_f32 v115, v116, v115, v121
	v_div_scale_f32 v116, s[52:53], v114, v114, v120
	v_rcp_f32_e32 v117, v116
	s_nop 0
	v_fma_f32 v118, -v116, v117, 1.0
	v_fmac_f32_e32 v117, v118, v117
	v_div_scale_f32 v118, vcc, v120, v114, v120
	v_mul_f32_e32 v119, v118, v117
	v_fma_f32 v122, -v116, v119, v118
	v_fmac_f32_e32 v119, v122, v117
	v_fma_f32 v116, -v116, v119, v118
	v_div_fmas_f32 v116, v116, v117, v119
	v_div_fixup_f32 v114, v116, v114, v120
	v_pk_mul_f32 v[112:113], v[114:115], v[112:113]
	s_nop 0
	v_cvt_pk_bf16_f32 v112, v112, v113
	global_store_dword v[108:109], v112, off offset:0
	s_waitcnt vmcnt(27)
	v_lshlrev_b32_e32 v112, 16, v81
	v_lshlrev_b32_e32 v114, 16, v82
	v_lshlrev_b32_e32 v120, 16, v83
	v_and_b32_e32 v121, 0xffff0000, v83
	v_and_b32_e32 v113, 0xffff0000, v81
	v_and_b32_e32 v115, 0xffff0000, v82
	v_pk_add_f32 v[112:113], v[112:113], v[114:115]
	s_nop 0
	v_pk_mul_f32 v[114:115], v[112:113], v[112:113]
	s_nop 0
	v_add_f32_e32 v114, v114, v115
	s_nop 1
	v_add_f32_dpp v114, v114, v114 quad_perm:[1,0,3,2] row_mask:0xf bank_mask:0xf
	s_nop 1
	v_add_f32_dpp v114, v114, v114 quad_perm:[2,3,0,1] row_mask:0xf bank_mask:0xf
	s_nop 1
	v_add_f32_dpp v114, v114, v114 row_half_mirror row_mask:0xf bank_mask:0xf
	s_nop 1
	v_add_f32_dpp v114, v114, v114 row_mirror row_mask:0xf bank_mask:0xf
	v_mov_b32_e32 v115, v114
	s_nop 1
	v_permlane16_swap_b32_e32 v114, v115
	v_add_f32_e32 v114, v114, v115
	v_mov_b32_e32 v115, v114
	s_nop 1
	v_permlane32_swap_b32_e32 v114, v115
	v_add_f32_e32 v114, v114, v115
	v_fmamk_f32 v114, v114, 0x3c000000, v231
	v_cmp_gt_f32_e32 vcc, s3, v114
	v_mul_f32_e32 v115, 0x4b800000, v114
	s_nop 0
	v_cndmask_b32_e32 v114, v114, v115, vcc
	v_rsq_f32_e32 v114, v114
	s_nop 0
	v_mul_f32_e32 v115, 0x45800000, v114
	v_cndmask_b32_e32 v114, v114, v115, vcc
	v_mul_f32_e32 v115, 0xbfb8aa3b, v120
	v_pk_mul_f32 v[112:113], v[112:113], v[114:115] op_sel_hi:[1,0]
	v_mul_f32_e32 v114, 0xbfb8aa3b, v121
	v_exp_f32_e32 v118, v115
	v_exp_f32_e32 v119, v114
	v_pk_mul_f32 v[112:113], v[102:103], v[112:113]
	v_pk_add_f32 v[114:115], v[118:119], 1.0 op_sel_hi:[1,0]
	s_nop 0
	v_div_scale_f32 v116, s[52:53], v115, v115, v121
	v_rcp_f32_e32 v117, v116
	s_nop 0
	v_fma_f32 v118, -v116, v117, 1.0
	v_fmac_f32_e32 v117, v118, v117
	v_div_scale_f32 v118, vcc, v121, v115, v121
	v_mul_f32_e32 v119, v118, v117
	v_fma_f32 v122, -v116, v119, v118
	v_fmac_f32_e32 v119, v122, v117
	v_fma_f32 v116, -v116, v119, v118
	v_div_fmas_f32 v116, v116, v117, v119
	v_div_fixup_f32 v115, v116, v115, v121
	v_div_scale_f32 v116, s[52:53], v114, v114, v120
	v_rcp_f32_e32 v117, v116
	s_nop 0
	v_fma_f32 v118, -v116, v117, 1.0
	v_fmac_f32_e32 v117, v118, v117
	v_div_scale_f32 v118, vcc, v120, v114, v120
	v_mul_f32_e32 v119, v118, v117
	v_fma_f32 v122, -v116, v119, v118
	v_fmac_f32_e32 v119, v122, v117
	v_fma_f32 v116, -v116, v119, v118
	v_div_fmas_f32 v116, v116, v117, v119
	v_div_fixup_f32 v114, v116, v114, v120
	v_pk_mul_f32 v[112:113], v[114:115], v[112:113]
	s_nop 0
	v_cvt_pk_bf16_f32 v112, v112, v113
	global_store_dword v[108:109], v112, off offset:256
	s_waitcnt vmcnt(25)
	v_lshlrev_b32_e32 v112, 16, v84
	v_lshlrev_b32_e32 v114, 16, v85
	v_lshlrev_b32_e32 v120, 16, v86
	v_and_b32_e32 v121, 0xffff0000, v86
	v_and_b32_e32 v113, 0xffff0000, v84
	v_and_b32_e32 v115, 0xffff0000, v85
	v_pk_add_f32 v[112:113], v[112:113], v[114:115]
	s_nop 0
	v_pk_mul_f32 v[114:115], v[112:113], v[112:113]
	s_nop 0
	v_add_f32_e32 v114, v114, v115
	s_nop 1
	v_add_f32_dpp v114, v114, v114 quad_perm:[1,0,3,2] row_mask:0xf bank_mask:0xf
	s_nop 1
	v_add_f32_dpp v114, v114, v114 quad_perm:[2,3,0,1] row_mask:0xf bank_mask:0xf
	s_nop 1
	v_add_f32_dpp v114, v114, v114 row_half_mirror row_mask:0xf bank_mask:0xf
	s_nop 1
	v_add_f32_dpp v114, v114, v114 row_mirror row_mask:0xf bank_mask:0xf
	v_mov_b32_e32 v115, v114
	s_nop 1
	v_permlane16_swap_b32_e32 v114, v115
	v_add_f32_e32 v114, v114, v115
	v_mov_b32_e32 v115, v114
	s_nop 1
	v_permlane32_swap_b32_e32 v114, v115
	v_add_f32_e32 v114, v114, v115
	v_fmamk_f32 v114, v114, 0x3c000000, v231
	v_cmp_gt_f32_e32 vcc, s3, v114
	v_mul_f32_e32 v115, 0x4b800000, v114
	s_nop 0
	v_cndmask_b32_e32 v114, v114, v115, vcc
	v_rsq_f32_e32 v114, v114
	s_nop 0
	v_mul_f32_e32 v115, 0x45800000, v114
	v_cndmask_b32_e32 v114, v114, v115, vcc
	v_mul_f32_e32 v115, 0xbfb8aa3b, v120
	v_pk_mul_f32 v[112:113], v[112:113], v[114:115] op_sel_hi:[1,0]
	v_mul_f32_e32 v114, 0xbfb8aa3b, v121
	v_exp_f32_e32 v118, v115
	v_exp_f32_e32 v119, v114
	v_pk_mul_f32 v[112:113], v[102:103], v[112:113]
	v_pk_add_f32 v[114:115], v[118:119], 1.0 op_sel_hi:[1,0]
	s_nop 0
	v_div_scale_f32 v116, s[52:53], v115, v115, v121
	v_rcp_f32_e32 v117, v116
	s_nop 0
	v_fma_f32 v118, -v116, v117, 1.0
	v_fmac_f32_e32 v117, v118, v117
	v_div_scale_f32 v118, vcc, v121, v115, v121
	v_mul_f32_e32 v119, v118, v117
	v_fma_f32 v122, -v116, v119, v118
	v_fmac_f32_e32 v119, v122, v117
	v_fma_f32 v116, -v116, v119, v118
	v_div_fmas_f32 v116, v116, v117, v119
	v_div_fixup_f32 v115, v116, v115, v121
	v_div_scale_f32 v116, s[52:53], v114, v114, v120
	v_rcp_f32_e32 v117, v116
	s_nop 0
	v_fma_f32 v118, -v116, v117, 1.0
	v_fmac_f32_e32 v117, v118, v117
	v_div_scale_f32 v118, vcc, v120, v114, v120
	v_mul_f32_e32 v119, v118, v117
	v_fma_f32 v122, -v116, v119, v118
	v_fmac_f32_e32 v119, v122, v117
	v_fma_f32 v116, -v116, v119, v118
	v_div_fmas_f32 v116, v116, v117, v119
	v_div_fixup_f32 v114, v116, v114, v120
	v_pk_mul_f32 v[112:113], v[114:115], v[112:113]
	s_nop 0
	v_cvt_pk_bf16_f32 v112, v112, v113
	global_store_dword v[108:109], v112, off offset:512
	s_waitcnt vmcnt(23)
	v_lshlrev_b32_e32 v112, 16, v87
	v_lshlrev_b32_e32 v114, 16, v88
	v_lshlrev_b32_e32 v120, 16, v89
	v_and_b32_e32 v121, 0xffff0000, v89
	v_and_b32_e32 v113, 0xffff0000, v87
	v_and_b32_e32 v115, 0xffff0000, v88
	v_pk_add_f32 v[112:113], v[112:113], v[114:115]
	s_nop 0
	v_pk_mul_f32 v[114:115], v[112:113], v[112:113]
	s_nop 0
	v_add_f32_e32 v114, v114, v115
	s_nop 1
	v_add_f32_dpp v114, v114, v114 quad_perm:[1,0,3,2] row_mask:0xf bank_mask:0xf
	s_nop 1
	v_add_f32_dpp v114, v114, v114 quad_perm:[2,3,0,1] row_mask:0xf bank_mask:0xf
	s_nop 1
	v_add_f32_dpp v114, v114, v114 row_half_mirror row_mask:0xf bank_mask:0xf
	s_nop 1
	v_add_f32_dpp v114, v114, v114 row_mirror row_mask:0xf bank_mask:0xf
	v_mov_b32_e32 v115, v114
	s_nop 1
	v_permlane16_swap_b32_e32 v114, v115
	v_add_f32_e32 v114, v114, v115
	v_mov_b32_e32 v115, v114
	s_nop 1
	v_permlane32_swap_b32_e32 v114, v115
	v_add_f32_e32 v114, v114, v115
	v_fmamk_f32 v114, v114, 0x3c000000, v231
	v_cmp_gt_f32_e32 vcc, s3, v114
	v_mul_f32_e32 v115, 0x4b800000, v114
	s_nop 0
	v_cndmask_b32_e32 v114, v114, v115, vcc
	v_rsq_f32_e32 v114, v114
	s_nop 0
	v_mul_f32_e32 v115, 0x45800000, v114
	v_cndmask_b32_e32 v114, v114, v115, vcc
	v_mul_f32_e32 v115, 0xbfb8aa3b, v120
	v_pk_mul_f32 v[112:113], v[112:113], v[114:115] op_sel_hi:[1,0]
	v_mul_f32_e32 v114, 0xbfb8aa3b, v121
	v_exp_f32_e32 v118, v115
	v_exp_f32_e32 v119, v114
	v_pk_mul_f32 v[112:113], v[102:103], v[112:113]
	v_pk_add_f32 v[114:115], v[118:119], 1.0 op_sel_hi:[1,0]
	s_nop 0
	v_div_scale_f32 v116, s[52:53], v115, v115, v121
	v_rcp_f32_e32 v117, v116
	s_nop 0
	v_fma_f32 v118, -v116, v117, 1.0
	v_fmac_f32_e32 v117, v118, v117
	v_div_scale_f32 v118, vcc, v121, v115, v121
	v_mul_f32_e32 v119, v118, v117
	v_fma_f32 v122, -v116, v119, v118
	v_fmac_f32_e32 v119, v122, v117
	v_fma_f32 v116, -v116, v119, v118
	v_div_fmas_f32 v116, v116, v117, v119
	v_div_fixup_f32 v115, v116, v115, v121
	v_div_scale_f32 v116, s[52:53], v114, v114, v120
	v_rcp_f32_e32 v117, v116
	s_nop 0
	v_fma_f32 v118, -v116, v117, 1.0
	v_fmac_f32_e32 v117, v118, v117
	v_div_scale_f32 v118, vcc, v120, v114, v120
	v_mul_f32_e32 v119, v118, v117
	v_fma_f32 v122, -v116, v119, v118
	v_fmac_f32_e32 v119, v122, v117
	v_fma_f32 v116, -v116, v119, v118
	v_div_fmas_f32 v116, v116, v117, v119
	v_div_fixup_f32 v114, v116, v114, v120
	v_pk_mul_f32 v[112:113], v[114:115], v[112:113]
	s_nop 0
	v_cvt_pk_bf16_f32 v112, v112, v113
	global_store_dword v[108:109], v112, off offset:768
	s_waitcnt vmcnt(21)
	v_lshlrev_b32_e32 v112, 16, v90
	v_lshlrev_b32_e32 v114, 16, v91
	v_lshlrev_b32_e32 v120, 16, v92
	v_and_b32_e32 v121, 0xffff0000, v92
	v_and_b32_e32 v113, 0xffff0000, v90
	v_and_b32_e32 v115, 0xffff0000, v91
	v_pk_add_f32 v[112:113], v[112:113], v[114:115]
	s_nop 0
	v_pk_mul_f32 v[114:115], v[112:113], v[112:113]
	s_nop 0
	v_add_f32_e32 v114, v114, v115
	s_nop 1
	v_add_f32_dpp v114, v114, v114 quad_perm:[1,0,3,2] row_mask:0xf bank_mask:0xf
	s_nop 1
	v_add_f32_dpp v114, v114, v114 quad_perm:[2,3,0,1] row_mask:0xf bank_mask:0xf
	s_nop 1
	v_add_f32_dpp v114, v114, v114 row_half_mirror row_mask:0xf bank_mask:0xf
	s_nop 1
	v_add_f32_dpp v114, v114, v114 row_mirror row_mask:0xf bank_mask:0xf
	v_mov_b32_e32 v115, v114
	s_nop 1
	v_permlane16_swap_b32_e32 v114, v115
	v_add_f32_e32 v114, v114, v115
	v_mov_b32_e32 v115, v114
	s_nop 1
	v_permlane32_swap_b32_e32 v114, v115
	v_add_f32_e32 v114, v114, v115
	v_fmamk_f32 v114, v114, 0x3c000000, v231
	v_cmp_gt_f32_e32 vcc, s3, v114
	v_mul_f32_e32 v115, 0x4b800000, v114
	s_nop 0
	v_cndmask_b32_e32 v114, v114, v115, vcc
	v_rsq_f32_e32 v114, v114
	s_nop 0
	v_mul_f32_e32 v115, 0x45800000, v114
	v_cndmask_b32_e32 v114, v114, v115, vcc
	v_mul_f32_e32 v115, 0xbfb8aa3b, v120
	v_pk_mul_f32 v[112:113], v[112:113], v[114:115] op_sel_hi:[1,0]
	v_mul_f32_e32 v114, 0xbfb8aa3b, v121
	v_exp_f32_e32 v118, v115
	v_exp_f32_e32 v119, v114
	v_pk_mul_f32 v[112:113], v[102:103], v[112:113]
	v_pk_add_f32 v[114:115], v[118:119], 1.0 op_sel_hi:[1,0]
	s_nop 0
	v_div_scale_f32 v116, s[52:53], v115, v115, v121
	v_rcp_f32_e32 v117, v116
	s_nop 0
	v_fma_f32 v118, -v116, v117, 1.0
	v_fmac_f32_e32 v117, v118, v117
	v_div_scale_f32 v118, vcc, v121, v115, v121
	v_mul_f32_e32 v119, v118, v117
	v_fma_f32 v122, -v116, v119, v118
	v_fmac_f32_e32 v119, v122, v117
	v_fma_f32 v116, -v116, v119, v118
	v_div_fmas_f32 v116, v116, v117, v119
	v_div_fixup_f32 v115, v116, v115, v121
	v_div_scale_f32 v116, s[52:53], v114, v114, v120
	v_rcp_f32_e32 v117, v116
	s_nop 0
	v_fma_f32 v118, -v116, v117, 1.0
	v_fmac_f32_e32 v117, v118, v117
	v_div_scale_f32 v118, vcc, v120, v114, v120
	v_mul_f32_e32 v119, v118, v117
	v_fma_f32 v122, -v116, v119, v118
	v_fmac_f32_e32 v119, v122, v117
	v_fma_f32 v116, -v116, v119, v118
	v_div_fmas_f32 v116, v116, v117, v119
	v_div_fixup_f32 v114, v116, v114, v120
	v_pk_mul_f32 v[112:113], v[114:115], v[112:113]
	s_nop 0
	v_cvt_pk_bf16_f32 v112, v112, v113
	global_store_dword v[110:111], v112, off offset:0
	s_waitcnt vmcnt(19)
	v_lshlrev_b32_e32 v112, 16, v93
	v_lshlrev_b32_e32 v114, 16, v94
	v_lshlrev_b32_e32 v120, 16, v95
	v_and_b32_e32 v121, 0xffff0000, v95
	v_and_b32_e32 v113, 0xffff0000, v93
	v_and_b32_e32 v115, 0xffff0000, v94
	v_pk_add_f32 v[112:113], v[112:113], v[114:115]
	s_nop 0
	v_pk_mul_f32 v[114:115], v[112:113], v[112:113]
	s_nop 0
	v_add_f32_e32 v114, v114, v115
	s_nop 1
	v_add_f32_dpp v114, v114, v114 quad_perm:[1,0,3,2] row_mask:0xf bank_mask:0xf
	s_nop 1
	v_add_f32_dpp v114, v114, v114 quad_perm:[2,3,0,1] row_mask:0xf bank_mask:0xf
	s_nop 1
	v_add_f32_dpp v114, v114, v114 row_half_mirror row_mask:0xf bank_mask:0xf
	s_nop 1
	v_add_f32_dpp v114, v114, v114 row_mirror row_mask:0xf bank_mask:0xf
	v_mov_b32_e32 v115, v114
	s_nop 1
	v_permlane16_swap_b32_e32 v114, v115
	v_add_f32_e32 v114, v114, v115
	v_mov_b32_e32 v115, v114
	s_nop 1
	v_permlane32_swap_b32_e32 v114, v115
	v_add_f32_e32 v114, v114, v115
	v_fmamk_f32 v114, v114, 0x3c000000, v231
	v_cmp_gt_f32_e32 vcc, s3, v114
	v_mul_f32_e32 v115, 0x4b800000, v114
	s_nop 0
	v_cndmask_b32_e32 v114, v114, v115, vcc
	v_rsq_f32_e32 v114, v114
	s_nop 0
	v_mul_f32_e32 v115, 0x45800000, v114
	v_cndmask_b32_e32 v114, v114, v115, vcc
	v_mul_f32_e32 v115, 0xbfb8aa3b, v120
	v_pk_mul_f32 v[112:113], v[112:113], v[114:115] op_sel_hi:[1,0]
	v_mul_f32_e32 v114, 0xbfb8aa3b, v121
	v_exp_f32_e32 v118, v115
	v_exp_f32_e32 v119, v114
	v_pk_mul_f32 v[112:113], v[102:103], v[112:113]
	v_pk_add_f32 v[114:115], v[118:119], 1.0 op_sel_hi:[1,0]
	s_nop 0
	v_div_scale_f32 v116, s[52:53], v115, v115, v121
	v_rcp_f32_e32 v117, v116
	s_nop 0
	v_fma_f32 v118, -v116, v117, 1.0
	v_fmac_f32_e32 v117, v118, v117
	v_div_scale_f32 v118, vcc, v121, v115, v121
	v_mul_f32_e32 v119, v118, v117
	v_fma_f32 v122, -v116, v119, v118
	v_fmac_f32_e32 v119, v122, v117
	v_fma_f32 v116, -v116, v119, v118
	v_div_fmas_f32 v116, v116, v117, v119
	v_div_fixup_f32 v115, v116, v115, v121
	v_div_scale_f32 v116, s[52:53], v114, v114, v120
	v_rcp_f32_e32 v117, v116
	s_nop 0
	v_fma_f32 v118, -v116, v117, 1.0
	v_fmac_f32_e32 v117, v118, v117
	v_div_scale_f32 v118, vcc, v120, v114, v120
	v_mul_f32_e32 v119, v118, v117
	v_fma_f32 v122, -v116, v119, v118
	v_fmac_f32_e32 v119, v122, v117
	v_fma_f32 v116, -v116, v119, v118
	v_div_fmas_f32 v116, v116, v117, v119
	v_div_fixup_f32 v114, v116, v114, v120
	v_pk_mul_f32 v[112:113], v[114:115], v[112:113]
	s_nop 0
	v_cvt_pk_bf16_f32 v112, v112, v113
	global_store_dword v[110:111], v112, off offset:256
	s_waitcnt vmcnt(17)
	v_lshlrev_b32_e32 v112, 16, v96
	v_lshlrev_b32_e32 v114, 16, v97
	v_lshlrev_b32_e32 v120, 16, v98
	v_and_b32_e32 v121, 0xffff0000, v98
	v_and_b32_e32 v113, 0xffff0000, v96
	v_and_b32_e32 v115, 0xffff0000, v97
	v_pk_add_f32 v[112:113], v[112:113], v[114:115]
	s_nop 0
	v_pk_mul_f32 v[114:115], v[112:113], v[112:113]
	s_nop 0
	v_add_f32_e32 v114, v114, v115
	s_nop 1
	v_add_f32_dpp v114, v114, v114 quad_perm:[1,0,3,2] row_mask:0xf bank_mask:0xf
	s_nop 1
	v_add_f32_dpp v114, v114, v114 quad_perm:[2,3,0,1] row_mask:0xf bank_mask:0xf
	s_nop 1
	v_add_f32_dpp v114, v114, v114 row_half_mirror row_mask:0xf bank_mask:0xf
	s_nop 1
	v_add_f32_dpp v114, v114, v114 row_mirror row_mask:0xf bank_mask:0xf
	v_mov_b32_e32 v115, v114
	s_nop 1
	v_permlane16_swap_b32_e32 v114, v115
	v_add_f32_e32 v114, v114, v115
	v_mov_b32_e32 v115, v114
	s_nop 1
	v_permlane32_swap_b32_e32 v114, v115
	v_add_f32_e32 v114, v114, v115
	v_fmamk_f32 v114, v114, 0x3c000000, v231
	v_cmp_gt_f32_e32 vcc, s3, v114
	v_mul_f32_e32 v115, 0x4b800000, v114
	s_nop 0
	v_cndmask_b32_e32 v114, v114, v115, vcc
	v_rsq_f32_e32 v114, v114
	s_nop 0
	v_mul_f32_e32 v115, 0x45800000, v114
	v_cndmask_b32_e32 v114, v114, v115, vcc
	v_mul_f32_e32 v115, 0xbfb8aa3b, v120
	v_pk_mul_f32 v[112:113], v[112:113], v[114:115] op_sel_hi:[1,0]
	v_mul_f32_e32 v114, 0xbfb8aa3b, v121
	v_exp_f32_e32 v118, v115
	v_exp_f32_e32 v119, v114
	v_pk_mul_f32 v[112:113], v[102:103], v[112:113]
	v_pk_add_f32 v[114:115], v[118:119], 1.0 op_sel_hi:[1,0]
	s_nop 0
	v_div_scale_f32 v116, s[52:53], v115, v115, v121
	v_rcp_f32_e32 v117, v116
	s_nop 0
	v_fma_f32 v118, -v116, v117, 1.0
	v_fmac_f32_e32 v117, v118, v117
	v_div_scale_f32 v118, vcc, v121, v115, v121
	v_mul_f32_e32 v119, v118, v117
	v_fma_f32 v122, -v116, v119, v118
	v_fmac_f32_e32 v119, v122, v117
	v_fma_f32 v116, -v116, v119, v118
	v_div_fmas_f32 v116, v116, v117, v119
	v_div_fixup_f32 v115, v116, v115, v121
	v_div_scale_f32 v116, s[52:53], v114, v114, v120
	v_rcp_f32_e32 v117, v116
	s_nop 0
	v_fma_f32 v118, -v116, v117, 1.0
	v_fmac_f32_e32 v117, v118, v117
	v_div_scale_f32 v118, vcc, v120, v114, v120
	v_mul_f32_e32 v119, v118, v117
	v_fma_f32 v122, -v116, v119, v118
	v_fmac_f32_e32 v119, v122, v117
	v_fma_f32 v116, -v116, v119, v118
	v_div_fmas_f32 v116, v116, v117, v119
	v_div_fixup_f32 v114, v116, v114, v120
	v_pk_mul_f32 v[112:113], v[114:115], v[112:113]
	s_nop 0
	v_cvt_pk_bf16_f32 v112, v112, v113
	global_store_dword v[110:111], v112, off offset:512
	s_waitcnt vmcnt(15)
	v_lshlrev_b32_e32 v112, 16, v99
	v_lshlrev_b32_e32 v114, 16, v100
	v_lshlrev_b32_e32 v120, 16, v101
	v_and_b32_e32 v121, 0xffff0000, v101
	v_and_b32_e32 v113, 0xffff0000, v99
	v_and_b32_e32 v115, 0xffff0000, v100
	v_pk_add_f32 v[112:113], v[112:113], v[114:115]
	s_nop 0
	v_pk_mul_f32 v[114:115], v[112:113], v[112:113]
	s_nop 0
	v_add_f32_e32 v114, v114, v115
	s_nop 1
	v_add_f32_dpp v114, v114, v114 quad_perm:[1,0,3,2] row_mask:0xf bank_mask:0xf
	s_nop 1
	v_add_f32_dpp v114, v114, v114 quad_perm:[2,3,0,1] row_mask:0xf bank_mask:0xf
	s_nop 1
	v_add_f32_dpp v114, v114, v114 row_half_mirror row_mask:0xf bank_mask:0xf
	s_nop 1
	v_add_f32_dpp v114, v114, v114 row_mirror row_mask:0xf bank_mask:0xf
	v_mov_b32_e32 v115, v114
	s_nop 1
	v_permlane16_swap_b32_e32 v114, v115
	v_add_f32_e32 v114, v114, v115
	v_mov_b32_e32 v115, v114
	s_nop 1
	v_permlane32_swap_b32_e32 v114, v115
	v_add_f32_e32 v114, v114, v115
	v_fmamk_f32 v114, v114, 0x3c000000, v231
	v_cmp_gt_f32_e32 vcc, s3, v114
	v_mul_f32_e32 v115, 0x4b800000, v114
	s_nop 0
	v_cndmask_b32_e32 v114, v114, v115, vcc
	v_rsq_f32_e32 v114, v114
	s_nop 0
	v_mul_f32_e32 v115, 0x45800000, v114
	v_cndmask_b32_e32 v114, v114, v115, vcc
	v_mul_f32_e32 v115, 0xbfb8aa3b, v120
	v_pk_mul_f32 v[112:113], v[112:113], v[114:115] op_sel_hi:[1,0]
	v_mul_f32_e32 v114, 0xbfb8aa3b, v121
	v_exp_f32_e32 v118, v115
	v_exp_f32_e32 v119, v114
	v_pk_mul_f32 v[112:113], v[102:103], v[112:113]
	v_pk_add_f32 v[114:115], v[118:119], 1.0 op_sel_hi:[1,0]
	s_nop 0
	v_div_scale_f32 v116, s[52:53], v115, v115, v121
	v_rcp_f32_e32 v117, v116
	s_nop 0
	v_fma_f32 v118, -v116, v117, 1.0
	v_fmac_f32_e32 v117, v118, v117
	v_div_scale_f32 v118, vcc, v121, v115, v121
	v_mul_f32_e32 v119, v118, v117
	v_fma_f32 v122, -v116, v119, v118
	v_fmac_f32_e32 v119, v122, v117
	v_fma_f32 v116, -v116, v119, v118
	v_div_fmas_f32 v116, v116, v117, v119
	v_div_fixup_f32 v115, v116, v115, v121
	v_div_scale_f32 v116, s[52:53], v114, v114, v120
	v_rcp_f32_e32 v117, v116
	s_nop 0
	v_fma_f32 v118, -v116, v117, 1.0
	v_fmac_f32_e32 v117, v118, v117
	v_div_scale_f32 v118, vcc, v120, v114, v120
	v_mul_f32_e32 v119, v118, v117
	v_fma_f32 v122, -v116, v119, v118
	v_fmac_f32_e32 v119, v122, v117
	v_fma_f32 v116, -v116, v119, v118
	v_div_fmas_f32 v116, v116, v117, v119
	v_div_fixup_f32 v114, v116, v114, v120
	v_pk_mul_f32 v[112:113], v[114:115], v[112:113]
	s_nop 0
	v_cvt_pk_bf16_f32 v112, v112, v113
	global_store_dword v[110:111], v112, off offset:768
	s_branch .LBB0_875
	s_branch .LBB0_883
